# merged the two closing waits of each K-loop load segment into one s_waitcnt vmcnt(8) lgkmcnt(0)
# baseline (speedup 1.0000x reference)
; #define PG8_LAS __attribute__((address_space(3)))
; #define PG8_STAGE(bufoff, gbase, voff) do { _Pragma("unroll") for (int _i = 0; _i < 2; ++_i) \
;         __builtin_amdgcn_global_load_lds((const unsigned*)((const char*)(gbase) + (voff)[_i]), (PG8_LAS unsigned*)(lds + (bufoff) + ldsw + _i * 8192), 16, 0, 0); } while (0)
; #define PG8_LDA(dst, b, h) do { _Pragma("unroll") for (int m = 0; m < 4; ++m) _Pragma("unroll") for (int k = 0; k < 2; ++k) dst[m][k] = *(const PG8_LAS bf16x8*)(lds + PG8_SA(b, h) + aoff + m * 2048 + k * 1024); } while (0)
; #define PG8_LDB(dst, b, h) do { _Pragma("unroll") for (int n = 0; n < 2; ++n) _Pragma("unroll") for (int k = 0; k < 2; ++k) dst[n][k] = *(const PG8_LAS bf16x8*)(lds + PG8_SB(b, h) + boff + n * 2048 + k * 1024); } while (0)
; #define PG8_WAIT_V(n) asm volatile("s_waitcnt vmcnt(" #n ")" ::: "memory")
; #define PG8_WAIT_L(n) asm volatile("s_waitcnt lgkmcnt(" #n ")" ::: "memory")
; #define PG8_BAR __builtin_amdgcn_s_barrier()
; #define PG8_SCHED __builtin_amdgcn_sched_barrier(0)
; template <class Epi, class Sched, bool ALIGN_EPI = false, bool SP2 = false>
; __device__ __forceinline__ void gemm_phase(PG8_LAS unsigned char* lds, const Gemm g, const Sched& S, const Epi& E, int wave_s) {
;     ...
;             const bool last = (t == nt - 2);
;             if constexpr (Epi::NEED_RS) { if (t == 0 && wid < 4) __builtin_amdgcn_global_load_lds((const unsigned*)(E.rstd + cur.pm * BM + wid * 64 + lane), (PG8_LAS unsigned*)(rsl + wid * 64), 4, 0, 0); }
;             const char* a1 = cA + (size_t)(t + 1) * kstep;
;             const char* a2 = last ? nA : cA + (size_t)(t + 2) * kstep; const char* b2 = last ? nB : cB + (size_t)(t + 2) * kstep;
;             const char* a3 = a2 + kstep; const char* b3 = b2 + kstep;
;             if (last && has_next) S.a_ready(nxt);
;             if constexpr (SP2) {
;             PG8_LDB(B0, 0, 0); PG8_LDB(B1, 0, 1); PG8_SCHED; PG8_LDA(At, 0, 0); PG8_STAGE(PG8_SA(1, 1), a1 + hstep, voffA);
;             PG8_WAIT_V(8); PG8_WAIT_L(0); PG8_BAR; PG8_MMA(0, 0, At, B0); PG8_MMA(0, 1, At, B1); PG8_BAR; PG8_SCHED;
;             PG8_LDA(At, 0, 1); PG8_STAGE(PG8_SB(0, 0), b2, voffB); PG8_STAGE(PG8_SB(0, 1), b2 + hstep, voffB); PG8_STAGE(PG8_SA(0, 0), a2, voffA);
;             PG8_WAIT_V(8); PG8_WAIT_L(0); PG8_BAR; PG8_MMA(1, 0, At, B0); PG8_MMA(1, 1, At, B1); PG8_BAR; PG8_SCHED;
.LBB0_41:
	ds_read_b128 v[144:147], v158 offset:3072
	ds_read_b128 v[148:151], v158 offset:2048
	ds_read_b128 v[152:155], v158 offset:1024
	ds_read_b128 v[160:163], v158
	ds_read_b128 v[164:167], v157 offset:3072
	ds_read_b128 v[168:171], v157 offset:2048
	ds_read_b128 v[172:175], v157 offset:1024
	ds_read_b128 v[176:179], v157
	s_add_u32 s48, s46, 0xfff00080
	s_addc_u32 s49, s47, -1
	s_cmp_eq_u32 s86, 60
	s_cselect_b32 s51, s31, s49
	s_cselect_b32 s50, s72, s48
	s_cselect_b32 s49, s35, s85
	s_cselect_b32 s48, s73, s84
	s_mov_b32 m0, s74
	s_nop 0
	ds_read_b128 v[180:183], v159
	ds_read_b128 v[184:187], v159 offset:1024
	ds_read_b128 v[188:191], v159 offset:2048
	ds_read_b128 v[192:195], v159 offset:3072
	ds_read_b128 v[196:199], v159 offset:4096
	ds_read_b128 v[200:203], v159 offset:5120
	ds_read_b128 v[204:207], v159 offset:6144
	ds_read_b128 v[208:211], v159 offset:7168
	global_load_lds_dwordx4 v138, s[46:47]
	s_mov_b32 m0, s75
	s_nop 0
	global_load_lds_dwordx4 v140, s[46:47]
	s_waitcnt vmcnt(8) lgkmcnt(0)
	s_barrier
	v_mfma_f32_16x16x32_bf16 v[124:127], v[176:179], v[180:183], v[124:127]
	v_mfma_f32_16x16x32_bf16 v[124:127], v[172:175], v[184:187], v[124:127]
	v_mfma_f32_16x16x32_bf16 v[120:123], v[164:167], v[184:187], v[120:123]
	v_mfma_f32_16x16x32_bf16 v[120:123], v[168:171], v[180:183], v[120:123]
	v_mfma_f32_16x16x32_bf16 v[104:107], v[168:171], v[188:191], v[104:107]
	v_mfma_f32_16x16x32_bf16 v[104:107], v[164:167], v[192:195], v[104:107]
	v_mfma_f32_16x16x32_bf16 v[108:111], v[172:175], v[192:195], v[108:111]
	v_mfma_f32_16x16x32_bf16 v[108:111], v[176:179], v[188:191], v[108:111]
	v_mfma_f32_16x16x32_bf16 v[92:95], v[176:179], v[196:199], v[92:95]
	v_mfma_f32_16x16x32_bf16 v[92:95], v[172:175], v[200:203], v[92:95]
	v_mfma_f32_16x16x32_bf16 v[88:91], v[164:167], v[200:203], v[88:91]
	v_mfma_f32_16x16x32_bf16 v[88:91], v[168:171], v[196:199], v[88:91]
	v_mfma_f32_16x16x32_bf16 v[56:59], v[168:171], v[204:207], v[56:59]
	v_mfma_f32_16x16x32_bf16 v[56:59], v[164:167], v[208:211], v[56:59]
	v_mfma_f32_16x16x32_bf16 v[64:67], v[172:175], v[208:211], v[64:67]
	v_mfma_f32_16x16x32_bf16 v[64:67], v[176:179], v[204:207], v[64:67]
	v_mfma_f32_16x16x32_bf16 v[116:119], v[160:163], v[180:183], v[116:119]
	v_mfma_f32_16x16x32_bf16 v[116:119], v[152:155], v[184:187], v[116:119]
	v_mfma_f32_16x16x32_bf16 v[112:115], v[144:147], v[184:187], v[112:115]
	v_mfma_f32_16x16x32_bf16 v[112:115], v[148:151], v[180:183], v[112:115]
	v_mfma_f32_16x16x32_bf16 v[96:99], v[148:151], v[188:191], v[96:99]
	v_mfma_f32_16x16x32_bf16 v[96:99], v[144:147], v[192:195], v[96:99]
	v_mfma_f32_16x16x32_bf16 v[100:103], v[152:155], v[192:195], v[100:103]
	v_mfma_f32_16x16x32_bf16 v[100:103], v[160:163], v[188:191], v[100:103]
	v_mfma_f32_16x16x32_bf16 v[84:87], v[160:163], v[196:199], v[84:87]
	v_mfma_f32_16x16x32_bf16 v[84:87], v[152:155], v[200:203], v[84:87]
	v_mfma_f32_16x16x32_bf16 v[80:83], v[144:147], v[200:203], v[80:83]
	v_mfma_f32_16x16x32_bf16 v[80:83], v[148:151], v[196:199], v[80:83]
	v_mfma_f32_16x16x32_bf16 v[48:51], v[148:151], v[204:207], v[48:51]
	v_mfma_f32_16x16x32_bf16 v[48:51], v[144:147], v[208:211], v[48:51]
	v_mfma_f32_16x16x32_bf16 v[52:55], v[152:155], v[208:211], v[52:55]
	v_mfma_f32_16x16x32_bf16 v[52:55], v[160:163], v[204:207], v[52:55]
	s_barrier
	s_mov_b32 m0, s76
	s_nop 0
	s_add_u32 s88, s48, 0x100000
	ds_read_b128 v[180:183], v159 offset:16384
	ds_read_b128 v[184:187], v159 offset:17408
	ds_read_b128 v[188:191], v159 offset:18432
	ds_read_b128 v[192:195], v159 offset:19456
	ds_read_b128 v[196:199], v159 offset:20480
	ds_read_b128 v[200:203], v159 offset:21504
	ds_read_b128 v[204:207], v159 offset:22528
	ds_read_b128 v[208:211], v159 offset:23552
	global_load_lds_dwordx4 v132, s[48:49]
	s_mov_b32 m0, s77
	s_addc_u32 s89, s49, 0
	global_load_lds_dwordx4 v128, s[48:49]
	s_mov_b32 m0, s78
	s_nop 0
	global_load_lds_dwordx4 v132, s[88:89]
	s_mov_b32 m0, s79
	s_nop 0
	global_load_lds_dwordx4 v128, s[88:89]
	s_mov_b32 m0, s43
	s_nop 0
	global_load_lds_dwordx4 v134, s[50:51]
	s_mov_b32 m0, s57
	s_nop 0
	global_load_lds_dwordx4 v130, s[50:51]
	s_waitcnt vmcnt(8) lgkmcnt(0)
	s_barrier
	v_mfma_f32_16x16x32_bf16 v[76:79], v[176:179], v[180:183], v[76:79]
	v_mfma_f32_16x16x32_bf16 v[76:79], v[172:175], v[184:187], v[76:79]
	v_mfma_f32_16x16x32_bf16 v[72:75], v[164:167], v[184:187], v[72:75]
	v_mfma_f32_16x16x32_bf16 v[72:75], v[168:171], v[180:183], v[72:75]
	v_mfma_f32_16x16x32_bf16 v[40:43], v[168:171], v[188:191], v[40:43]
	v_mfma_f32_16x16x32_bf16 v[40:43], v[164:167], v[192:195], v[40:43]
	v_mfma_f32_16x16x32_bf16 v[44:47], v[172:175], v[192:195], v[44:47]
	v_mfma_f32_16x16x32_bf16 v[44:47], v[176:179], v[188:191], v[44:47]
	v_mfma_f32_16x16x32_bf16 v[28:31], v[176:179], v[196:199], v[28:31]
	v_mfma_f32_16x16x32_bf16 v[28:31], v[172:175], v[200:203], v[28:31]
	v_mfma_f32_16x16x32_bf16 v[24:27], v[164:167], v[200:203], v[24:27]
	v_mfma_f32_16x16x32_bf16 v[24:27], v[168:171], v[196:199], v[24:27]
	v_mfma_f32_16x16x32_bf16 v[8:11], v[168:171], v[204:207], v[8:11]
	v_mfma_f32_16x16x32_bf16 v[8:11], v[164:167], v[208:211], v[8:11]
	v_mfma_f32_16x16x32_bf16 v[12:15], v[172:175], v[208:211], v[12:15]
	v_mfma_f32_16x16x32_bf16 v[12:15], v[176:179], v[204:207], v[12:15]
	v_mfma_f32_16x16x32_bf16 v[68:71], v[160:163], v[180:183], v[68:71]
	v_mfma_f32_16x16x32_bf16 v[68:71], v[152:155], v[184:187], v[68:71]
	v_mfma_f32_16x16x32_bf16 v[60:63], v[144:147], v[184:187], v[60:63]
	v_mfma_f32_16x16x32_bf16 v[60:63], v[148:151], v[180:183], v[60:63]
	v_mfma_f32_16x16x32_bf16 v[32:35], v[148:151], v[188:191], v[32:35]
	v_mfma_f32_16x16x32_bf16 v[32:35], v[144:147], v[192:195], v[32:35]
	v_mfma_f32_16x16x32_bf16 v[36:39], v[152:155], v[192:195], v[36:39]
	v_mfma_f32_16x16x32_bf16 v[36:39], v[160:163], v[188:191], v[36:39]
	v_mfma_f32_16x16x32_bf16 v[20:23], v[160:163], v[196:199], v[20:23]
	v_mfma_f32_16x16x32_bf16 v[20:23], v[152:155], v[200:203], v[20:23]
	v_mfma_f32_16x16x32_bf16 v[16:19], v[144:147], v[200:203], v[16:19]
	v_mfma_f32_16x16x32_bf16 v[16:19], v[148:151], v[196:199], v[16:19]
	v_mfma_f32_16x16x32_bf16 v[0:3], v[148:151], v[204:207], v[0:3]
	v_mfma_f32_16x16x32_bf16 v[0:3], v[144:147], v[208:211], v[0:3]
	v_mfma_f32_16x16x32_bf16 v[4:7], v[152:155], v[208:211], v[4:7]
	v_mfma_f32_16x16x32_bf16 v[4:7], v[160:163], v[204:207], v[4:7]
	s_barrier
; #define PG8_STAGE(bufoff, gbase, voff) do { _Pragma("unroll") for (int _i = 0; _i < 2; ++_i) \
;         __builtin_amdgcn_global_load_lds((const unsigned*)((const char*)(gbase) + (voff)[_i]), (PG8_LAS unsigned*)(lds + (bufoff) + ldsw + _i * 8192), 16, 0, 0); } while (0)
; #define PG8_LDA(dst, b, h) do { _Pragma("unroll") for (int m = 0; m < 4; ++m) _Pragma("unroll") for (int k = 0; k < 2; ++k) dst[m][k] = *(const PG8_LAS bf16x8*)(lds + PG8_SA(b, h) + aoff + m * 2048 + k * 1024); } while (0)
; #define PG8_LDB(dst, b, h) do { _Pragma("unroll") for (int n = 0; n < 2; ++n) _Pragma("unroll") for (int k = 0; k < 2; ++k) dst[n][k] = *(const PG8_LAS bf16x8*)(lds + PG8_SB(b, h) + boff + n * 2048 + k * 1024); } while (0)
; #define PG8_MMA(ai, bj, At, Bt) do { __builtin_amdgcn_s_setprio(1); _Pragma("unroll") for (int m = 0; m < 4; ++m) _Pragma("unroll") for (int n = 0; n < 2; ++n) _Pragma("unroll") for (int k = 0; k < 2; ++k) \
;         acc[ai][bj][m][n] = __builtin_amdgcn_mfma_f32_16x16x32_bf16(Bt[n][k], At[m][k], acc[ai][bj][m][n], 0, 0, 0); __builtin_amdgcn_s_setprio(0); } while (0)
; #define PG8_WAIT_V(n) asm volatile("s_waitcnt vmcnt(" #n ")" ::: "memory")
; #define PG8_WAIT_L(n) asm volatile("s_waitcnt lgkmcnt(" #n ")" ::: "memory")
; #define PG8_BAR __builtin_amdgcn_s_barrier()
; #define PG8_SCHED __builtin_amdgcn_sched_barrier(0)
; template <class Epi, class Sched, bool ALIGN_EPI = false, bool SP2 = false>
; __device__ __forceinline__ void gemm_phase(PG8_LAS unsigned char* lds, const Gemm g, const Sched& S, const Epi& E, int wave_s) {
;     ...
;             PG8_LDB(B0, 1, 0); PG8_LDB(B1, 1, 1); PG8_SCHED; PG8_LDA(At, 1, 0); PG8_STAGE(PG8_SA(0, 1), a2 + hstep, voffA);
;             PG8_WAIT_V(8); PG8_WAIT_L(0); PG8_BAR; PG8_MMA(0, 0, At, B0); PG8_MMA(0, 1, At, B1); PG8_BAR; PG8_SCHED;
;             PG8_LDA(At, 1, 1); PG8_STAGE(PG8_SB(1, 0), b3, voffB); PG8_STAGE(PG8_SB(1, 1), b3 + hstep, voffB); PG8_STAGE(PG8_SA(1, 0), a3, voffA);
;             PG8_WAIT_V(8); PG8_WAIT_L(0); PG8_BAR; PG8_MMA(1, 0, At, B0); PG8_MMA(1, 1, At, B1); PG8_BAR; PG8_SCHED;
	ds_read_b128 v[144:147], v142
	ds_read_b128 v[148:151], v142 offset:1024
	ds_read_b128 v[152:155], v142 offset:2048
	ds_read_b128 v[160:163], v142 offset:3072
	ds_read_b128 v[164:167], v143
	ds_read_b128 v[168:171], v143 offset:1024
	ds_read_b128 v[172:175], v143 offset:2048
	ds_read_b128 v[176:179], v143 offset:3072
	s_add_u32 s50, s50, 0x100000
	s_addc_u32 s51, s51, 0
	s_mov_b32 m0, s58
	s_nop 0
	ds_read_b128 v[180:183], v159 offset:32768
	ds_read_b128 v[184:187], v159 offset:33792
	ds_read_b128 v[188:191], v159 offset:34816
	ds_read_b128 v[192:195], v159 offset:35840
	ds_read_b128 v[196:199], v159 offset:36864
	ds_read_b128 v[200:203], v159 offset:37888
	ds_read_b128 v[204:207], v159 offset:38912
	ds_read_b128 v[208:211], v159 offset:39936
	global_load_lds_dwordx4 v134, s[50:51]
	s_mov_b32 m0, s59
	s_nop 0
	global_load_lds_dwordx4 v130, s[50:51]
	s_waitcnt vmcnt(8) lgkmcnt(0)
	s_barrier
	v_mfma_f32_16x16x32_bf16 v[124:127], v[144:147], v[180:183], v[124:127]
	v_mfma_f32_16x16x32_bf16 v[124:127], v[148:151], v[184:187], v[124:127]
	v_mfma_f32_16x16x32_bf16 v[120:123], v[160:163], v[184:187], v[120:123]
	v_mfma_f32_16x16x32_bf16 v[120:123], v[152:155], v[180:183], v[120:123]
	v_mfma_f32_16x16x32_bf16 v[104:107], v[152:155], v[188:191], v[104:107]
	v_mfma_f32_16x16x32_bf16 v[104:107], v[160:163], v[192:195], v[104:107]
	v_mfma_f32_16x16x32_bf16 v[108:111], v[148:151], v[192:195], v[108:111]
	v_mfma_f32_16x16x32_bf16 v[108:111], v[144:147], v[188:191], v[108:111]
	v_mfma_f32_16x16x32_bf16 v[92:95], v[144:147], v[196:199], v[92:95]
	v_mfma_f32_16x16x32_bf16 v[92:95], v[148:151], v[200:203], v[92:95]
	v_mfma_f32_16x16x32_bf16 v[88:91], v[160:163], v[200:203], v[88:91]
	v_mfma_f32_16x16x32_bf16 v[88:91], v[152:155], v[196:199], v[88:91]
	v_mfma_f32_16x16x32_bf16 v[56:59], v[152:155], v[204:207], v[56:59]
	v_mfma_f32_16x16x32_bf16 v[56:59], v[160:163], v[208:211], v[56:59]
	v_mfma_f32_16x16x32_bf16 v[64:67], v[148:151], v[208:211], v[64:67]
	v_mfma_f32_16x16x32_bf16 v[64:67], v[144:147], v[204:207], v[64:67]
	v_mfma_f32_16x16x32_bf16 v[116:119], v[164:167], v[180:183], v[116:119]
	v_mfma_f32_16x16x32_bf16 v[116:119], v[168:171], v[184:187], v[116:119]
	v_mfma_f32_16x16x32_bf16 v[112:115], v[176:179], v[184:187], v[112:115]
	v_mfma_f32_16x16x32_bf16 v[112:115], v[172:175], v[180:183], v[112:115]
	v_mfma_f32_16x16x32_bf16 v[96:99], v[172:175], v[188:191], v[96:99]
	v_mfma_f32_16x16x32_bf16 v[96:99], v[176:179], v[192:195], v[96:99]
	v_mfma_f32_16x16x32_bf16 v[100:103], v[168:171], v[192:195], v[100:103]
	v_mfma_f32_16x16x32_bf16 v[100:103], v[164:167], v[188:191], v[100:103]
	v_mfma_f32_16x16x32_bf16 v[84:87], v[164:167], v[196:199], v[84:87]
	v_mfma_f32_16x16x32_bf16 v[84:87], v[168:171], v[200:203], v[84:87]
	v_mfma_f32_16x16x32_bf16 v[80:83], v[176:179], v[200:203], v[80:83]
	v_mfma_f32_16x16x32_bf16 v[80:83], v[172:175], v[196:199], v[80:83]
	v_mfma_f32_16x16x32_bf16 v[48:51], v[172:175], v[204:207], v[48:51]
	v_mfma_f32_16x16x32_bf16 v[48:51], v[176:179], v[208:211], v[48:51]
	v_mfma_f32_16x16x32_bf16 v[52:55], v[168:171], v[208:211], v[52:55]
	v_mfma_f32_16x16x32_bf16 v[52:55], v[164:167], v[204:207], v[52:55]
	s_barrier
	s_mov_b32 m0, s80
	s_nop 0
	s_add_u32 s94, s48, 0x80
	s_addc_u32 s95, s49, 0
	s_add_u32 s48, s48, 0x100080
	ds_read_b128 v[180:183], v159 offset:49152
	ds_read_b128 v[184:187], v159 offset:50176
	ds_read_b128 v[188:191], v159 offset:51200
	ds_read_b128 v[192:195], v159 offset:52224
	ds_read_b128 v[196:199], v159 offset:53248
	ds_read_b128 v[200:203], v159 offset:54272
	ds_read_b128 v[204:207], v159 offset:55296
	ds_read_b128 v[208:211], v159 offset:56320
	global_load_lds_dwordx4 v132, s[94:95]
	s_mov_b32 m0, s81
	s_addc_u32 s49, s49, 0
	global_load_lds_dwordx4 v128, s[94:95]
	s_mov_b32 m0, s82
	s_nop 0
	global_load_lds_dwordx4 v132, s[48:49]
	s_mov_b32 m0, s83
	s_nop 0
	global_load_lds_dwordx4 v128, s[48:49]
	s_mov_b32 m0, s64
	s_nop 0
	s_add_u32 s96, s50, 0xfff00080
	s_addc_u32 s97, s51, -1
	global_load_lds_dwordx4 v134, s[96:97]
	s_mov_b32 m0, s65
	s_nop 0
	global_load_lds_dwordx4 v130, s[96:97]
	s_waitcnt vmcnt(8) lgkmcnt(0)
	s_barrier
	v_mfma_f32_16x16x32_bf16 v[76:79], v[144:147], v[180:183], v[76:79]
	v_mfma_f32_16x16x32_bf16 v[76:79], v[148:151], v[184:187], v[76:79]
	v_mfma_f32_16x16x32_bf16 v[72:75], v[160:163], v[184:187], v[72:75]
	v_mfma_f32_16x16x32_bf16 v[72:75], v[152:155], v[180:183], v[72:75]
	v_mfma_f32_16x16x32_bf16 v[40:43], v[152:155], v[188:191], v[40:43]
	v_mfma_f32_16x16x32_bf16 v[40:43], v[160:163], v[192:195], v[40:43]
	v_mfma_f32_16x16x32_bf16 v[44:47], v[148:151], v[192:195], v[44:47]
	v_mfma_f32_16x16x32_bf16 v[44:47], v[144:147], v[188:191], v[44:47]
	v_mfma_f32_16x16x32_bf16 v[28:31], v[144:147], v[196:199], v[28:31]
	v_mfma_f32_16x16x32_bf16 v[28:31], v[148:151], v[200:203], v[28:31]
	v_mfma_f32_16x16x32_bf16 v[24:27], v[160:163], v[200:203], v[24:27]
	v_mfma_f32_16x16x32_bf16 v[24:27], v[152:155], v[196:199], v[24:27]
	v_mfma_f32_16x16x32_bf16 v[8:11], v[152:155], v[204:207], v[8:11]
	v_mfma_f32_16x16x32_bf16 v[8:11], v[160:163], v[208:211], v[8:11]
	v_mfma_f32_16x16x32_bf16 v[12:15], v[148:151], v[208:211], v[12:15]
	v_mfma_f32_16x16x32_bf16 v[12:15], v[144:147], v[204:207], v[12:15]
	v_mfma_f32_16x16x32_bf16 v[68:71], v[164:167], v[180:183], v[68:71]
	v_mfma_f32_16x16x32_bf16 v[68:71], v[168:171], v[184:187], v[68:71]
	v_mfma_f32_16x16x32_bf16 v[60:63], v[176:179], v[184:187], v[60:63]
	v_mfma_f32_16x16x32_bf16 v[60:63], v[172:175], v[180:183], v[60:63]
	v_mfma_f32_16x16x32_bf16 v[32:35], v[172:175], v[188:191], v[32:35]
	v_mfma_f32_16x16x32_bf16 v[32:35], v[176:179], v[192:195], v[32:35]
	v_mfma_f32_16x16x32_bf16 v[36:39], v[168:171], v[192:195], v[36:39]
	v_mfma_f32_16x16x32_bf16 v[36:39], v[164:167], v[188:191], v[36:39]
	v_mfma_f32_16x16x32_bf16 v[20:23], v[164:167], v[196:199], v[20:23]
	v_mfma_f32_16x16x32_bf16 v[20:23], v[168:171], v[200:203], v[20:23]
	v_mfma_f32_16x16x32_bf16 v[16:19], v[176:179], v[200:203], v[16:19]
	v_mfma_f32_16x16x32_bf16 v[16:19], v[172:175], v[196:199], v[16:19]
	v_mfma_f32_16x16x32_bf16 v[0:3], v[172:175], v[204:207], v[0:3]
	v_mfma_f32_16x16x32_bf16 v[0:3], v[176:179], v[208:211], v[0:3]
	v_mfma_f32_16x16x32_bf16 v[4:7], v[168:171], v[208:211], v[4:7]
	v_mfma_f32_16x16x32_bf16 v[4:7], v[164:167], v[204:207], v[4:7]
	s_barrier
	s_add_i32 s86, s86, 2
	s_add_u32 s46, s46, 0x100
	s_addc_u32 s47, s47, 0
	s_add_u32 s84, s84, 0x100
	s_addc_u32 s85, s85, 0
	s_cmp_gt_u32 s86, 61
	s_cbranch_scc0 .LBB0_41
	s_and_b64 vcc, exec, s[14:15]
	s_cbranch_vccz .LBB0_44
	s_barrier

; #define PG8_LAS __attribute__((address_space(3)))
; #define PG8_STAGE(bufoff, gbase, voff) do { _Pragma("unroll") for (int _i = 0; _i < 2; ++_i) \
;         __builtin_amdgcn_global_load_lds((const unsigned*)((const char*)(gbase) + (voff)[_i]), (PG8_LAS unsigned*)(lds + (bufoff) + ldsw + _i * 8192), 16, 0, 0); } while (0)
; #define PG8_LDA(dst, b, h) do { _Pragma("unroll") for (int m = 0; m < 4; ++m) _Pragma("unroll") for (int k = 0; k < 2; ++k) dst[m][k] = *(const PG8_LAS bf16x8*)(lds + PG8_SA(b, h) + aoff + m * 2048 + k * 1024); } while (0)
; #define PG8_LDB(dst, b, h) do { _Pragma("unroll") for (int n = 0; n < 2; ++n) _Pragma("unroll") for (int k = 0; k < 2; ++k) dst[n][k] = *(const PG8_LAS bf16x8*)(lds + PG8_SB(b, h) + boff + n * 2048 + k * 1024); } while (0)
; #define PG8_WAIT_V(n) asm volatile("s_waitcnt vmcnt(" #n ")" ::: "memory")
; #define PG8_WAIT_L(n) asm volatile("s_waitcnt lgkmcnt(" #n ")" ::: "memory")
; #define PG8_BAR __builtin_amdgcn_s_barrier()
; #define PG8_SCHED __builtin_amdgcn_sched_barrier(0)
; template <class Epi, class Sched, bool ALIGN_EPI = false, bool SP2 = false>
; __device__ __forceinline__ void gemm_phase(PG8_LAS unsigned char* lds, const Gemm g, const Sched& S, const Epi& E, int wave_s) {
;     ...
;             const bool last = (t == nt - 2);
;             if constexpr (Epi::NEED_RS) { if (t == 0 && wid < 4) __builtin_amdgcn_global_load_lds((const unsigned*)(E.rstd + cur.pm * BM + wid * 64 + lane), (PG8_LAS unsigned*)(rsl + wid * 64), 4, 0, 0); }
;             const char* a1 = cA + (size_t)(t + 1) * kstep;
;             const char* a2 = last ? nA : cA + (size_t)(t + 2) * kstep; const char* b2 = last ? nB : cB + (size_t)(t + 2) * kstep;
;             const char* a3 = a2 + kstep; const char* b3 = b2 + kstep;
;             if (last && has_next) S.a_ready(nxt);
;             if constexpr (SP2) {
;             PG8_LDB(B0, 0, 0); PG8_LDB(B1, 0, 1); PG8_SCHED; PG8_LDA(At, 0, 0); PG8_STAGE(PG8_SA(1, 1), a1 + hstep, voffA);
;             PG8_WAIT_V(8); PG8_WAIT_L(0); PG8_BAR; PG8_MMA(0, 0, At, B0); PG8_MMA(0, 1, At, B1); PG8_BAR; PG8_SCHED;
;             PG8_LDA(At, 0, 1); PG8_STAGE(PG8_SB(0, 0), b2, voffB); PG8_STAGE(PG8_SB(0, 1), b2 + hstep, voffB); PG8_STAGE(PG8_SA(0, 0), a2, voffA);
;             PG8_WAIT_V(8); PG8_WAIT_L(0); PG8_BAR; PG8_MMA(1, 0, At, B0); PG8_MMA(1, 1, At, B1); PG8_BAR; PG8_SCHED;
.LBB0_1200:
	ds_read_b128 v[128:131], v211
	ds_read_b128 v[132:135], v211 offset:1024
	ds_read_b128 v[136:139], v211 offset:2048
	ds_read_b128 v[140:143], v211 offset:3072
	ds_read_b128 v[144:147], v212
	ds_read_b128 v[148:151], v212 offset:1024
	ds_read_b128 v[152:155], v212 offset:2048
	ds_read_b128 v[156:159], v212 offset:3072
	s_add_u32 s45, s50, 0xfff00080
	s_addc_u32 s52, s51, -1
	s_cmp_eq_u32 s85, s43
	s_cselect_b32 s55, s47, s52
	s_cselect_b32 s54, s46, s45
	s_cselect_b32 s53, s49, s41
	s_cselect_b32 s52, s48, s7
	s_add_i32 m0, s9, 0xc000
	ds_read_b128 v[160:163], v213
	ds_read_b128 v[164:167], v213 offset:1024
	ds_read_b128 v[168:171], v213 offset:2048
	ds_read_b128 v[172:175], v213 offset:3072
	ds_read_b128 v[176:179], v213 offset:4096
	ds_read_b128 v[180:183], v213 offset:5120
	ds_read_b128 v[196:199], v213 offset:6144
	ds_read_b128 v[200:203], v213 offset:7168
	global_load_lds_dwordx4 v192, s[50:51]
	s_add_i32 m0, s9, 0xe000
	s_nop 0
	global_load_lds_dwordx4 v194, s[50:51]
	s_waitcnt vmcnt(8) lgkmcnt(0)
	s_barrier
	v_mfma_f32_16x16x32_bf16 v[124:127], v[128:131], v[160:163], v[124:127]
	v_mfma_f32_16x16x32_bf16 v[124:127], v[132:135], v[164:167], v[124:127]
	v_mfma_f32_16x16x32_bf16 v[120:123], v[140:143], v[164:167], v[120:123]
	v_mfma_f32_16x16x32_bf16 v[120:123], v[136:139], v[160:163], v[120:123]
	v_mfma_f32_16x16x32_bf16 v[104:107], v[136:139], v[168:171], v[104:107]
	v_mfma_f32_16x16x32_bf16 v[104:107], v[140:143], v[172:175], v[104:107]
	v_mfma_f32_16x16x32_bf16 v[108:111], v[132:135], v[172:175], v[108:111]
	v_mfma_f32_16x16x32_bf16 v[108:111], v[128:131], v[168:171], v[108:111]
	v_mfma_f32_16x16x32_bf16 v[92:95], v[128:131], v[176:179], v[92:95]
	v_mfma_f32_16x16x32_bf16 v[92:95], v[132:135], v[180:183], v[92:95]
	v_mfma_f32_16x16x32_bf16 v[88:91], v[140:143], v[180:183], v[88:91]
	v_mfma_f32_16x16x32_bf16 v[88:91], v[136:139], v[176:179], v[88:91]
	v_mfma_f32_16x16x32_bf16 v[72:75], v[136:139], v[196:199], v[72:75]
	v_mfma_f32_16x16x32_bf16 v[72:75], v[140:143], v[200:203], v[72:75]
	v_mfma_f32_16x16x32_bf16 v[76:79], v[132:135], v[200:203], v[76:79]
	v_mfma_f32_16x16x32_bf16 v[76:79], v[128:131], v[196:199], v[76:79]
	v_mfma_f32_16x16x32_bf16 v[116:119], v[144:147], v[160:163], v[116:119]
	v_mfma_f32_16x16x32_bf16 v[116:119], v[148:151], v[164:167], v[116:119]
	v_mfma_f32_16x16x32_bf16 v[112:115], v[156:159], v[164:167], v[112:115]
	v_mfma_f32_16x16x32_bf16 v[112:115], v[152:155], v[160:163], v[112:115]
	v_mfma_f32_16x16x32_bf16 v[96:99], v[152:155], v[168:171], v[96:99]
	v_mfma_f32_16x16x32_bf16 v[96:99], v[156:159], v[172:175], v[96:99]
	v_mfma_f32_16x16x32_bf16 v[100:103], v[148:151], v[172:175], v[100:103]
	v_mfma_f32_16x16x32_bf16 v[100:103], v[144:147], v[168:171], v[100:103]
	v_mfma_f32_16x16x32_bf16 v[84:87], v[144:147], v[176:179], v[84:87]
	v_mfma_f32_16x16x32_bf16 v[84:87], v[148:151], v[180:183], v[84:87]
	v_mfma_f32_16x16x32_bf16 v[80:83], v[156:159], v[180:183], v[80:83]
	v_mfma_f32_16x16x32_bf16 v[80:83], v[152:155], v[176:179], v[80:83]
	v_mfma_f32_16x16x32_bf16 v[64:67], v[152:155], v[196:199], v[64:67]
	v_mfma_f32_16x16x32_bf16 v[64:67], v[156:159], v[200:203], v[64:67]
	v_mfma_f32_16x16x32_bf16 v[68:71], v[148:151], v[200:203], v[68:71]
	v_mfma_f32_16x16x32_bf16 v[68:71], v[144:147], v[196:199], v[68:71]
	s_barrier
	s_add_i32 s45, s75, s60
	s_mov_b32 m0, s45
	ds_read_b128 v[160:163], v213 offset:16384
	ds_read_b128 v[164:167], v213 offset:17408
	ds_read_b128 v[168:171], v213 offset:18432
	ds_read_b128 v[172:175], v213 offset:19456
	ds_read_b128 v[176:179], v213 offset:20480
	ds_read_b128 v[180:183], v213 offset:21504
	ds_read_b128 v[196:199], v213 offset:22528
	ds_read_b128 v[200:203], v213 offset:23552
	global_load_lds_dwordx4 v186, s[52:53]
	s_add_i32 m0, s45, 0x2000
	s_add_u32 s86, s52, 0x100000
	s_addc_u32 s87, s53, 0
	s_add_i32 s45, s76, s60
	global_load_lds_dwordx4 v190, s[52:53]
	s_mov_b32 m0, s45
	s_nop 0
	global_load_lds_dwordx4 v186, s[86:87]
	s_add_i32 m0, s45, 0x2000
	s_nop 0
	global_load_lds_dwordx4 v190, s[86:87]
	s_mov_b32 m0, s9
	s_nop 0
	global_load_lds_dwordx4 v184, s[54:55]
	s_mov_b32 m0, s61
	s_nop 0
	global_load_lds_dwordx4 v188, s[54:55]
	s_waitcnt vmcnt(8) lgkmcnt(0)
	s_barrier
	v_mfma_f32_16x16x32_bf16 v[60:63], v[128:131], v[160:163], v[60:63]
	v_mfma_f32_16x16x32_bf16 v[60:63], v[132:135], v[164:167], v[60:63]
	v_mfma_f32_16x16x32_bf16 v[56:59], v[140:143], v[164:167], v[56:59]
	v_mfma_f32_16x16x32_bf16 v[56:59], v[136:139], v[160:163], v[56:59]
	v_mfma_f32_16x16x32_bf16 v[40:43], v[136:139], v[168:171], v[40:43]
	v_mfma_f32_16x16x32_bf16 v[40:43], v[140:143], v[172:175], v[40:43]
	v_mfma_f32_16x16x32_bf16 v[44:47], v[132:135], v[172:175], v[44:47]
	v_mfma_f32_16x16x32_bf16 v[44:47], v[128:131], v[168:171], v[44:47]
	v_mfma_f32_16x16x32_bf16 v[28:31], v[128:131], v[176:179], v[28:31]
	v_mfma_f32_16x16x32_bf16 v[28:31], v[132:135], v[180:183], v[28:31]
	v_mfma_f32_16x16x32_bf16 v[24:27], v[140:143], v[180:183], v[24:27]
	v_mfma_f32_16x16x32_bf16 v[24:27], v[136:139], v[176:179], v[24:27]
	v_mfma_f32_16x16x32_bf16 v[8:11], v[136:139], v[196:199], v[8:11]
	v_mfma_f32_16x16x32_bf16 v[8:11], v[140:143], v[200:203], v[8:11]
	v_mfma_f32_16x16x32_bf16 v[12:15], v[132:135], v[200:203], v[12:15]
	v_mfma_f32_16x16x32_bf16 v[12:15], v[128:131], v[196:199], v[12:15]
	v_mfma_f32_16x16x32_bf16 v[52:55], v[144:147], v[160:163], v[52:55]
	v_mfma_f32_16x16x32_bf16 v[52:55], v[148:151], v[164:167], v[52:55]
	v_mfma_f32_16x16x32_bf16 v[48:51], v[156:159], v[164:167], v[48:51]
	v_mfma_f32_16x16x32_bf16 v[48:51], v[152:155], v[160:163], v[48:51]
	v_mfma_f32_16x16x32_bf16 v[32:35], v[152:155], v[168:171], v[32:35]
	v_mfma_f32_16x16x32_bf16 v[32:35], v[156:159], v[172:175], v[32:35]
	v_mfma_f32_16x16x32_bf16 v[36:39], v[148:151], v[172:175], v[36:39]
	v_mfma_f32_16x16x32_bf16 v[36:39], v[144:147], v[168:171], v[36:39]
	v_mfma_f32_16x16x32_bf16 v[20:23], v[144:147], v[176:179], v[20:23]
	v_mfma_f32_16x16x32_bf16 v[20:23], v[148:151], v[180:183], v[20:23]
	v_mfma_f32_16x16x32_bf16 v[16:19], v[156:159], v[180:183], v[16:19]
	v_mfma_f32_16x16x32_bf16 v[16:19], v[152:155], v[176:179], v[16:19]
	v_mfma_f32_16x16x32_bf16 v[0:3], v[152:155], v[196:199], v[0:3]
	v_mfma_f32_16x16x32_bf16 v[0:3], v[156:159], v[200:203], v[0:3]
	v_mfma_f32_16x16x32_bf16 v[4:7], v[148:151], v[200:203], v[4:7]
	v_mfma_f32_16x16x32_bf16 v[4:7], v[144:147], v[196:199], v[4:7]
	s_barrier
; #define PG8_STAGE(bufoff, gbase, voff) do { _Pragma("unroll") for (int _i = 0; _i < 2; ++_i) \
;         __builtin_amdgcn_global_load_lds((const unsigned*)((const char*)(gbase) + (voff)[_i]), (PG8_LAS unsigned*)(lds + (bufoff) + ldsw + _i * 8192), 16, 0, 0); } while (0)
; #define PG8_LDA(dst, b, h) do { _Pragma("unroll") for (int m = 0; m < 4; ++m) _Pragma("unroll") for (int k = 0; k < 2; ++k) dst[m][k] = *(const PG8_LAS bf16x8*)(lds + PG8_SA(b, h) + aoff + m * 2048 + k * 1024); } while (0)
; #define PG8_LDB(dst, b, h) do { _Pragma("unroll") for (int n = 0; n < 2; ++n) _Pragma("unroll") for (int k = 0; k < 2; ++k) dst[n][k] = *(const PG8_LAS bf16x8*)(lds + PG8_SB(b, h) + boff + n * 2048 + k * 1024); } while (0)
; #define PG8_MMA(ai, bj, At, Bt) do { __builtin_amdgcn_s_setprio(1); _Pragma("unroll") for (int m = 0; m < 4; ++m) _Pragma("unroll") for (int n = 0; n < 2; ++n) _Pragma("unroll") for (int k = 0; k < 2; ++k) \
;         acc[ai][bj][m][n] = __builtin_amdgcn_mfma_f32_16x16x32_bf16(Bt[n][k], At[m][k], acc[ai][bj][m][n], 0, 0, 0); __builtin_amdgcn_s_setprio(0); } while (0)
; #define PG8_WAIT_V(n) asm volatile("s_waitcnt vmcnt(" #n ")" ::: "memory")
; #define PG8_WAIT_L(n) asm volatile("s_waitcnt lgkmcnt(" #n ")" ::: "memory")
; #define PG8_BAR __builtin_amdgcn_s_barrier()
; #define PG8_SCHED __builtin_amdgcn_sched_barrier(0)
; template <class Epi, class Sched, bool ALIGN_EPI = false, bool SP2 = false>
; __device__ __forceinline__ void gemm_phase(PG8_LAS unsigned char* lds, const Gemm g, const Sched& S, const Epi& E, int wave_s) {
;     ...
;             PG8_LDB(B0, 1, 0); PG8_LDB(B1, 1, 1); PG8_SCHED; PG8_LDA(At, 1, 0); PG8_STAGE(PG8_SA(0, 1), a2 + hstep, voffA);
;             PG8_WAIT_V(8); PG8_WAIT_L(0); PG8_BAR; PG8_MMA(0, 0, At, B0); PG8_MMA(0, 1, At, B1); PG8_BAR; PG8_SCHED;
;             PG8_LDA(At, 1, 1); PG8_STAGE(PG8_SB(1, 0), b3, voffB); PG8_STAGE(PG8_SB(1, 1), b3 + hstep, voffB); PG8_STAGE(PG8_SA(1, 0), a3, voffA);
;             PG8_WAIT_V(8); PG8_WAIT_L(0); PG8_BAR; PG8_MMA(1, 0, At, B0); PG8_MMA(1, 1, At, B1); PG8_BAR; PG8_SCHED;
	s_add_i32 s45, 0, 0x18000
	s_add_i32 s86, 0, 0x1c000
	v_add_u32_e32 v140, s45, v210
	v_add_u32_e32 v156, s86, v210
	ds_read_b128 v[128:131], v140
	ds_read_b128 v[132:135], v140 offset:1024
	ds_read_b128 v[136:139], v140 offset:2048
	ds_read_b128 v[140:143], v140 offset:3072
	ds_read_b128 v[144:147], v156
	ds_read_b128 v[148:151], v156 offset:1024
	ds_read_b128 v[152:155], v156 offset:2048
	ds_read_b128 v[156:159], v156 offset:3072
	s_add_u32 s54, s54, 0x100000
	s_addc_u32 s55, s55, 0
	s_mov_b32 m0, s62
	s_nop 0
	ds_read_b128 v[160:163], v213 offset:32768
	ds_read_b128 v[164:167], v213 offset:33792
	ds_read_b128 v[168:171], v213 offset:34816
	ds_read_b128 v[172:175], v213 offset:35840
	ds_read_b128 v[176:179], v213 offset:36864
	ds_read_b128 v[180:183], v213 offset:37888
	ds_read_b128 v[196:199], v213 offset:38912
	ds_read_b128 v[200:203], v213 offset:39936
	global_load_lds_dwordx4 v184, s[54:55]
	s_mov_b32 m0, s63
	s_nop 0
	global_load_lds_dwordx4 v188, s[54:55]
	s_waitcnt vmcnt(8) lgkmcnt(0)
	s_barrier
	v_mfma_f32_16x16x32_bf16 v[124:127], v[128:131], v[160:163], v[124:127]
	v_mfma_f32_16x16x32_bf16 v[124:127], v[132:135], v[164:167], v[124:127]
	v_mfma_f32_16x16x32_bf16 v[120:123], v[140:143], v[164:167], v[120:123]
	v_mfma_f32_16x16x32_bf16 v[120:123], v[136:139], v[160:163], v[120:123]
	v_mfma_f32_16x16x32_bf16 v[104:107], v[136:139], v[168:171], v[104:107]
	v_mfma_f32_16x16x32_bf16 v[104:107], v[140:143], v[172:175], v[104:107]
	v_mfma_f32_16x16x32_bf16 v[108:111], v[132:135], v[172:175], v[108:111]
	v_mfma_f32_16x16x32_bf16 v[108:111], v[128:131], v[168:171], v[108:111]
	v_mfma_f32_16x16x32_bf16 v[92:95], v[128:131], v[176:179], v[92:95]
	v_mfma_f32_16x16x32_bf16 v[92:95], v[132:135], v[180:183], v[92:95]
	v_mfma_f32_16x16x32_bf16 v[88:91], v[140:143], v[180:183], v[88:91]
	v_mfma_f32_16x16x32_bf16 v[88:91], v[136:139], v[176:179], v[88:91]
	v_mfma_f32_16x16x32_bf16 v[72:75], v[136:139], v[196:199], v[72:75]
	v_mfma_f32_16x16x32_bf16 v[72:75], v[140:143], v[200:203], v[72:75]
	v_mfma_f32_16x16x32_bf16 v[76:79], v[132:135], v[200:203], v[76:79]
	v_mfma_f32_16x16x32_bf16 v[76:79], v[128:131], v[196:199], v[76:79]
	v_mfma_f32_16x16x32_bf16 v[116:119], v[144:147], v[160:163], v[116:119]
	v_mfma_f32_16x16x32_bf16 v[116:119], v[148:151], v[164:167], v[116:119]
	v_mfma_f32_16x16x32_bf16 v[112:115], v[156:159], v[164:167], v[112:115]
	v_mfma_f32_16x16x32_bf16 v[112:115], v[152:155], v[160:163], v[112:115]
	v_mfma_f32_16x16x32_bf16 v[96:99], v[152:155], v[168:171], v[96:99]
	v_mfma_f32_16x16x32_bf16 v[96:99], v[156:159], v[172:175], v[96:99]
	v_mfma_f32_16x16x32_bf16 v[100:103], v[148:151], v[172:175], v[100:103]
	v_mfma_f32_16x16x32_bf16 v[100:103], v[144:147], v[168:171], v[100:103]
	v_mfma_f32_16x16x32_bf16 v[84:87], v[144:147], v[176:179], v[84:87]
	v_mfma_f32_16x16x32_bf16 v[84:87], v[148:151], v[180:183], v[84:87]
	v_mfma_f32_16x16x32_bf16 v[80:83], v[156:159], v[180:183], v[80:83]
	v_mfma_f32_16x16x32_bf16 v[80:83], v[152:155], v[176:179], v[80:83]
	v_mfma_f32_16x16x32_bf16 v[64:67], v[152:155], v[196:199], v[64:67]
	v_mfma_f32_16x16x32_bf16 v[64:67], v[156:159], v[200:203], v[64:67]
	v_mfma_f32_16x16x32_bf16 v[68:71], v[148:151], v[200:203], v[68:71]
	v_mfma_f32_16x16x32_bf16 v[68:71], v[144:147], v[196:199], v[68:71]
	s_barrier
	s_add_i32 s45, s45, s60
	s_mov_b32 m0, s45
	ds_read_b128 v[160:163], v213 offset:49152
	ds_read_b128 v[164:167], v213 offset:50176
	ds_read_b128 v[168:171], v213 offset:51200
	ds_read_b128 v[172:175], v213 offset:52224
	ds_read_b128 v[176:179], v213 offset:53248
	ds_read_b128 v[180:183], v213 offset:54272
	ds_read_b128 v[196:199], v213 offset:55296
	ds_read_b128 v[200:203], v213 offset:56320
	s_add_u32 s94, s52, 0x80
	s_addc_u32 s95, s53, 0
	global_load_lds_dwordx4 v186, s[94:95]
	s_add_i32 m0, s45, 0x2000
	s_add_u32 s52, s52, 0x100080
	s_addc_u32 s53, s53, 0
	s_add_i32 s45, s86, s60
	global_load_lds_dwordx4 v190, s[94:95]
	s_mov_b32 m0, s45
	s_nop 0
	global_load_lds_dwordx4 v186, s[52:53]
	s_add_i32 m0, s45, 0x2000
	s_nop 0
	global_load_lds_dwordx4 v190, s[52:53]
	s_mov_b32 m0, s70
	s_nop 0
	s_add_u32 s96, s54, 0xfff00080
	s_addc_u32 s97, s55, -1
	global_load_lds_dwordx4 v184, s[96:97]
	s_mov_b32 m0, s71
	s_nop 0
	global_load_lds_dwordx4 v188, s[96:97]
	s_waitcnt vmcnt(8) lgkmcnt(0)
	s_barrier
	v_mfma_f32_16x16x32_bf16 v[60:63], v[128:131], v[160:163], v[60:63]
	v_mfma_f32_16x16x32_bf16 v[60:63], v[132:135], v[164:167], v[60:63]
	v_mfma_f32_16x16x32_bf16 v[56:59], v[140:143], v[164:167], v[56:59]
	v_mfma_f32_16x16x32_bf16 v[56:59], v[136:139], v[160:163], v[56:59]
	v_mfma_f32_16x16x32_bf16 v[40:43], v[136:139], v[168:171], v[40:43]
	v_mfma_f32_16x16x32_bf16 v[40:43], v[140:143], v[172:175], v[40:43]
	v_mfma_f32_16x16x32_bf16 v[44:47], v[132:135], v[172:175], v[44:47]
	v_mfma_f32_16x16x32_bf16 v[44:47], v[128:131], v[168:171], v[44:47]
	v_mfma_f32_16x16x32_bf16 v[28:31], v[128:131], v[176:179], v[28:31]
	v_mfma_f32_16x16x32_bf16 v[28:31], v[132:135], v[180:183], v[28:31]
	v_mfma_f32_16x16x32_bf16 v[24:27], v[140:143], v[180:183], v[24:27]
	v_mfma_f32_16x16x32_bf16 v[24:27], v[136:139], v[176:179], v[24:27]
	v_mfma_f32_16x16x32_bf16 v[8:11], v[136:139], v[196:199], v[8:11]
	v_mfma_f32_16x16x32_bf16 v[8:11], v[140:143], v[200:203], v[8:11]
	v_mfma_f32_16x16x32_bf16 v[12:15], v[132:135], v[200:203], v[12:15]
	v_mfma_f32_16x16x32_bf16 v[12:15], v[128:131], v[196:199], v[12:15]
	v_mfma_f32_16x16x32_bf16 v[52:55], v[144:147], v[160:163], v[52:55]
	v_mfma_f32_16x16x32_bf16 v[52:55], v[148:151], v[164:167], v[52:55]
	v_mfma_f32_16x16x32_bf16 v[48:51], v[156:159], v[164:167], v[48:51]
	v_mfma_f32_16x16x32_bf16 v[48:51], v[152:155], v[160:163], v[48:51]
	v_mfma_f32_16x16x32_bf16 v[32:35], v[152:155], v[168:171], v[32:35]
	v_mfma_f32_16x16x32_bf16 v[32:35], v[156:159], v[172:175], v[32:35]
	v_mfma_f32_16x16x32_bf16 v[36:39], v[148:151], v[172:175], v[36:39]
	v_mfma_f32_16x16x32_bf16 v[36:39], v[144:147], v[168:171], v[36:39]
	v_mfma_f32_16x16x32_bf16 v[20:23], v[144:147], v[176:179], v[20:23]
	v_mfma_f32_16x16x32_bf16 v[20:23], v[148:151], v[180:183], v[20:23]
	v_mfma_f32_16x16x32_bf16 v[16:19], v[156:159], v[180:183], v[16:19]
	v_mfma_f32_16x16x32_bf16 v[16:19], v[152:155], v[176:179], v[16:19]
	v_mfma_f32_16x16x32_bf16 v[0:3], v[152:155], v[196:199], v[0:3]
	v_mfma_f32_16x16x32_bf16 v[0:3], v[156:159], v[200:203], v[0:3]
	v_mfma_f32_16x16x32_bf16 v[4:7], v[148:151], v[200:203], v[4:7]
	v_mfma_f32_16x16x32_bf16 v[4:7], v[144:147], v[196:199], v[4:7]
	s_barrier
	s_add_i32 s45, s43, 2
	s_add_u32 s50, s50, 0x100
	s_addc_u32 s51, s51, 0
	s_add_u32 s7, s7, 0x100
	s_addc_u32 s41, s41, 0
	s_cmp_ge_i32 s43, s85
	s_mov_b32 s43, s45
	s_cbranch_scc0 .LBB0_1200
	s_and_b64 vcc, exec, s[20:21]
	s_cbranch_vccz .LBB0_1203
	s_barrier

; #define PG8_LAS __attribute__((address_space(3)))
; #define PG8_STAGE(bufoff, gbase, voff) do { _Pragma("unroll") for (int _i = 0; _i < 2; ++_i) \
;         __builtin_amdgcn_global_load_lds((const unsigned*)((const char*)(gbase) + (voff)[_i]), (PG8_LAS unsigned*)(lds + (bufoff) + ldsw + _i * 8192), 16, 0, 0); } while (0)
; #define PG8_LDA(dst, b, h) do { _Pragma("unroll") for (int m = 0; m < 4; ++m) _Pragma("unroll") for (int k = 0; k < 2; ++k) dst[m][k] = *(const PG8_LAS bf16x8*)(lds + PG8_SA(b, h) + aoff + m * 2048 + k * 1024); } while (0)
; #define PG8_LDB(dst, b, h) do { _Pragma("unroll") for (int n = 0; n < 2; ++n) _Pragma("unroll") for (int k = 0; k < 2; ++k) dst[n][k] = *(const PG8_LAS bf16x8*)(lds + PG8_SB(b, h) + boff + n * 2048 + k * 1024); } while (0)
; #define PG8_WAIT_V(n) asm volatile("s_waitcnt vmcnt(" #n ")" ::: "memory")
; #define PG8_WAIT_L(n) asm volatile("s_waitcnt lgkmcnt(" #n ")" ::: "memory")
; #define PG8_BAR __builtin_amdgcn_s_barrier()
; #define PG8_SCHED __builtin_amdgcn_sched_barrier(0)
; template <class Epi, class Sched, bool ALIGN_EPI = false, bool SP2 = false>
; __device__ __forceinline__ void gemm_phase(PG8_LAS unsigned char* lds, const Gemm g, const Sched& S, const Epi& E, int wave_s) {
;     ...
;             const bool last = (t == nt - 2);
;             if constexpr (Epi::NEED_RS) { if (t == 0 && wid < 4) __builtin_amdgcn_global_load_lds((const unsigned*)(E.rstd + cur.pm * BM + wid * 64 + lane), (PG8_LAS unsigned*)(rsl + wid * 64), 4, 0, 0); }
;             const char* a1 = cA + (size_t)(t + 1) * kstep;
;             const char* a2 = last ? nA : cA + (size_t)(t + 2) * kstep; const char* b2 = last ? nB : cB + (size_t)(t + 2) * kstep;
;             const char* a3 = a2 + kstep; const char* b3 = b2 + kstep;
;             if (last && has_next) S.a_ready(nxt);
;             if constexpr (SP2) {
;             PG8_LDB(B0, 0, 0); PG8_LDB(B1, 0, 1); PG8_SCHED; PG8_LDA(At, 0, 0); PG8_STAGE(PG8_SA(1, 1), a1 + hstep, voffA);
;             PG8_WAIT_V(8); PG8_WAIT_L(0); PG8_BAR; PG8_MMA(0, 0, At, B0); PG8_MMA(0, 1, At, B1); PG8_BAR; PG8_SCHED;
;             PG8_LDA(At, 0, 1); PG8_STAGE(PG8_SB(0, 0), b2, voffB); PG8_STAGE(PG8_SB(0, 1), b2 + hstep, voffB); PG8_STAGE(PG8_SA(0, 0), a2, voffA);
;             PG8_WAIT_V(8); PG8_WAIT_L(0); PG8_BAR; PG8_MMA(1, 0, At, B0); PG8_MMA(1, 1, At, B1); PG8_BAR; PG8_SCHED;
.LBB0_1343:
	ds_read_b128 v[144:147], v150 offset:3072
	ds_read_b128 v[152:155], v150 offset:2048
	ds_read_b128 v[156:159], v150 offset:1024
	ds_read_b128 v[160:163], v150
	ds_read_b128 v[164:167], v149 offset:3072
	ds_read_b128 v[168:171], v149 offset:2048
	ds_read_b128 v[172:175], v149 offset:1024
	ds_read_b128 v[176:179], v149
	s_add_u32 s46, s44, 0xfff00080
	s_addc_u32 s47, s45, -1
	s_cmp_eq_u32 s88, 60
	s_cselect_b32 s49, s29, s47
	s_cselect_b32 s48, s74, s46
	s_cselect_b32 s47, s35, s87
	s_cselect_b32 s46, s75, s86
	s_mov_b32 m0, s76
	s_nop 0
	ds_read_b128 v[180:183], v151
	ds_read_b128 v[184:187], v151 offset:1024
	ds_read_b128 v[188:191], v151 offset:2048
	ds_read_b128 v[192:195], v151 offset:3072
	ds_read_b128 v[196:199], v151 offset:4096
	ds_read_b128 v[200:203], v151 offset:5120
	ds_read_b128 v[204:207], v151 offset:6144
	ds_read_b128 v[208:211], v151 offset:7168
	global_load_lds_dwordx4 v138, s[44:45]
	s_mov_b32 m0, s77
	s_nop 0
	global_load_lds_dwordx4 v140, s[44:45]
	s_waitcnt vmcnt(8) lgkmcnt(0)
	s_barrier
	v_mfma_f32_16x16x32_bf16 v[124:127], v[176:179], v[180:183], v[124:127]
	v_mfma_f32_16x16x32_bf16 v[124:127], v[172:175], v[184:187], v[124:127]
	v_mfma_f32_16x16x32_bf16 v[120:123], v[164:167], v[184:187], v[120:123]
	v_mfma_f32_16x16x32_bf16 v[120:123], v[168:171], v[180:183], v[120:123]
	v_mfma_f32_16x16x32_bf16 v[104:107], v[168:171], v[188:191], v[104:107]
	v_mfma_f32_16x16x32_bf16 v[104:107], v[164:167], v[192:195], v[104:107]
	v_mfma_f32_16x16x32_bf16 v[108:111], v[172:175], v[192:195], v[108:111]
	v_mfma_f32_16x16x32_bf16 v[108:111], v[176:179], v[188:191], v[108:111]
	v_mfma_f32_16x16x32_bf16 v[92:95], v[176:179], v[196:199], v[92:95]
	v_mfma_f32_16x16x32_bf16 v[92:95], v[172:175], v[200:203], v[92:95]
	v_mfma_f32_16x16x32_bf16 v[88:91], v[164:167], v[200:203], v[88:91]
	v_mfma_f32_16x16x32_bf16 v[88:91], v[168:171], v[196:199], v[88:91]
	v_mfma_f32_16x16x32_bf16 v[72:75], v[168:171], v[204:207], v[72:75]
	v_mfma_f32_16x16x32_bf16 v[72:75], v[164:167], v[208:211], v[72:75]
	v_mfma_f32_16x16x32_bf16 v[76:79], v[172:175], v[208:211], v[76:79]
	v_mfma_f32_16x16x32_bf16 v[76:79], v[176:179], v[204:207], v[76:79]
	v_mfma_f32_16x16x32_bf16 v[116:119], v[160:163], v[180:183], v[116:119]
	v_mfma_f32_16x16x32_bf16 v[116:119], v[156:159], v[184:187], v[116:119]
	v_mfma_f32_16x16x32_bf16 v[112:115], v[144:147], v[184:187], v[112:115]
	v_mfma_f32_16x16x32_bf16 v[112:115], v[152:155], v[180:183], v[112:115]
	v_mfma_f32_16x16x32_bf16 v[96:99], v[152:155], v[188:191], v[96:99]
	v_mfma_f32_16x16x32_bf16 v[96:99], v[144:147], v[192:195], v[96:99]
	v_mfma_f32_16x16x32_bf16 v[100:103], v[156:159], v[192:195], v[100:103]
	v_mfma_f32_16x16x32_bf16 v[100:103], v[160:163], v[188:191], v[100:103]
	v_mfma_f32_16x16x32_bf16 v[84:87], v[160:163], v[196:199], v[84:87]
	v_mfma_f32_16x16x32_bf16 v[84:87], v[156:159], v[200:203], v[84:87]
	v_mfma_f32_16x16x32_bf16 v[80:83], v[144:147], v[200:203], v[80:83]
	v_mfma_f32_16x16x32_bf16 v[80:83], v[152:155], v[196:199], v[80:83]
	v_mfma_f32_16x16x32_bf16 v[64:67], v[152:155], v[204:207], v[64:67]
	v_mfma_f32_16x16x32_bf16 v[64:67], v[144:147], v[208:211], v[64:67]
	v_mfma_f32_16x16x32_bf16 v[68:71], v[156:159], v[208:211], v[68:71]
	v_mfma_f32_16x16x32_bf16 v[68:71], v[160:163], v[204:207], v[68:71]
	s_barrier
	s_mov_b32 m0, s78
	s_nop 0
	s_add_u32 s90, s46, 0x100000
	ds_read_b128 v[180:183], v151 offset:16384
	ds_read_b128 v[184:187], v151 offset:17408
	ds_read_b128 v[188:191], v151 offset:18432
	ds_read_b128 v[192:195], v151 offset:19456
	ds_read_b128 v[196:199], v151 offset:20480
	ds_read_b128 v[200:203], v151 offset:21504
	ds_read_b128 v[204:207], v151 offset:22528
	ds_read_b128 v[208:211], v151 offset:23552
	global_load_lds_dwordx4 v132, s[46:47]
	s_mov_b32 m0, s79
	s_addc_u32 s91, s47, 0
	global_load_lds_dwordx4 v128, s[46:47]
	s_mov_b32 m0, s80
	s_nop 0
	global_load_lds_dwordx4 v132, s[90:91]
	s_mov_b32 m0, s81
	s_nop 0
	global_load_lds_dwordx4 v128, s[90:91]
	s_mov_b32 m0, s41
	s_nop 0
	global_load_lds_dwordx4 v134, s[48:49]
	s_mov_b32 m0, s43
	s_nop 0
	global_load_lds_dwordx4 v130, s[48:49]
	s_waitcnt vmcnt(8) lgkmcnt(0)
	s_barrier
	v_mfma_f32_16x16x32_bf16 v[60:63], v[176:179], v[180:183], v[60:63]
	v_mfma_f32_16x16x32_bf16 v[60:63], v[172:175], v[184:187], v[60:63]
	v_mfma_f32_16x16x32_bf16 v[56:59], v[164:167], v[184:187], v[56:59]
	v_mfma_f32_16x16x32_bf16 v[56:59], v[168:171], v[180:183], v[56:59]
	v_mfma_f32_16x16x32_bf16 v[40:43], v[168:171], v[188:191], v[40:43]
	v_mfma_f32_16x16x32_bf16 v[40:43], v[164:167], v[192:195], v[40:43]
	v_mfma_f32_16x16x32_bf16 v[44:47], v[172:175], v[192:195], v[44:47]
	v_mfma_f32_16x16x32_bf16 v[44:47], v[176:179], v[188:191], v[44:47]
	v_mfma_f32_16x16x32_bf16 v[28:31], v[176:179], v[196:199], v[28:31]
	v_mfma_f32_16x16x32_bf16 v[28:31], v[172:175], v[200:203], v[28:31]
	v_mfma_f32_16x16x32_bf16 v[24:27], v[164:167], v[200:203], v[24:27]
	v_mfma_f32_16x16x32_bf16 v[24:27], v[168:171], v[196:199], v[24:27]
	v_mfma_f32_16x16x32_bf16 v[8:11], v[168:171], v[204:207], v[8:11]
	v_mfma_f32_16x16x32_bf16 v[8:11], v[164:167], v[208:211], v[8:11]
	v_mfma_f32_16x16x32_bf16 v[12:15], v[172:175], v[208:211], v[12:15]
	v_mfma_f32_16x16x32_bf16 v[12:15], v[176:179], v[204:207], v[12:15]
	v_mfma_f32_16x16x32_bf16 v[52:55], v[160:163], v[180:183], v[52:55]
	v_mfma_f32_16x16x32_bf16 v[52:55], v[156:159], v[184:187], v[52:55]
	v_mfma_f32_16x16x32_bf16 v[48:51], v[144:147], v[184:187], v[48:51]
	v_mfma_f32_16x16x32_bf16 v[48:51], v[152:155], v[180:183], v[48:51]
	v_mfma_f32_16x16x32_bf16 v[32:35], v[152:155], v[188:191], v[32:35]
	v_mfma_f32_16x16x32_bf16 v[32:35], v[144:147], v[192:195], v[32:35]
	v_mfma_f32_16x16x32_bf16 v[36:39], v[156:159], v[192:195], v[36:39]
	v_mfma_f32_16x16x32_bf16 v[36:39], v[160:163], v[188:191], v[36:39]
	v_mfma_f32_16x16x32_bf16 v[20:23], v[160:163], v[196:199], v[20:23]
	v_mfma_f32_16x16x32_bf16 v[20:23], v[156:159], v[200:203], v[20:23]
	v_mfma_f32_16x16x32_bf16 v[16:19], v[144:147], v[200:203], v[16:19]
	v_mfma_f32_16x16x32_bf16 v[16:19], v[152:155], v[196:199], v[16:19]
	v_mfma_f32_16x16x32_bf16 v[0:3], v[152:155], v[204:207], v[0:3]
	v_mfma_f32_16x16x32_bf16 v[0:3], v[144:147], v[208:211], v[0:3]
	v_mfma_f32_16x16x32_bf16 v[4:7], v[156:159], v[208:211], v[4:7]
	v_mfma_f32_16x16x32_bf16 v[4:7], v[160:163], v[204:207], v[4:7]
	s_barrier
; #define PG8_STAGE(bufoff, gbase, voff) do { _Pragma("unroll") for (int _i = 0; _i < 2; ++_i) \
;         __builtin_amdgcn_global_load_lds((const unsigned*)((const char*)(gbase) + (voff)[_i]), (PG8_LAS unsigned*)(lds + (bufoff) + ldsw + _i * 8192), 16, 0, 0); } while (0)
; #define PG8_LDA(dst, b, h) do { _Pragma("unroll") for (int m = 0; m < 4; ++m) _Pragma("unroll") for (int k = 0; k < 2; ++k) dst[m][k] = *(const PG8_LAS bf16x8*)(lds + PG8_SA(b, h) + aoff + m * 2048 + k * 1024); } while (0)
; #define PG8_LDB(dst, b, h) do { _Pragma("unroll") for (int n = 0; n < 2; ++n) _Pragma("unroll") for (int k = 0; k < 2; ++k) dst[n][k] = *(const PG8_LAS bf16x8*)(lds + PG8_SB(b, h) + boff + n * 2048 + k * 1024); } while (0)
; #define PG8_MMA(ai, bj, At, Bt) do { __builtin_amdgcn_s_setprio(1); _Pragma("unroll") for (int m = 0; m < 4; ++m) _Pragma("unroll") for (int n = 0; n < 2; ++n) _Pragma("unroll") for (int k = 0; k < 2; ++k) \
;         acc[ai][bj][m][n] = __builtin_amdgcn_mfma_f32_16x16x32_bf16(Bt[n][k], At[m][k], acc[ai][bj][m][n], 0, 0, 0); __builtin_amdgcn_s_setprio(0); } while (0)
; #define PG8_WAIT_V(n) asm volatile("s_waitcnt vmcnt(" #n ")" ::: "memory")
; #define PG8_WAIT_L(n) asm volatile("s_waitcnt lgkmcnt(" #n ")" ::: "memory")
; #define PG8_BAR __builtin_amdgcn_s_barrier()
; #define PG8_SCHED __builtin_amdgcn_sched_barrier(0)
; template <class Epi, class Sched, bool ALIGN_EPI = false, bool SP2 = false>
; __device__ __forceinline__ void gemm_phase(PG8_LAS unsigned char* lds, const Gemm g, const Sched& S, const Epi& E, int wave_s) {
;     ...
;             PG8_LDB(B0, 1, 0); PG8_LDB(B1, 1, 1); PG8_SCHED; PG8_LDA(At, 1, 0); PG8_STAGE(PG8_SA(0, 1), a2 + hstep, voffA);
;             PG8_WAIT_V(8); PG8_WAIT_L(0); PG8_BAR; PG8_MMA(0, 0, At, B0); PG8_MMA(0, 1, At, B1); PG8_BAR; PG8_SCHED;
;             PG8_LDA(At, 1, 1); PG8_STAGE(PG8_SB(1, 0), b3, voffB); PG8_STAGE(PG8_SB(1, 1), b3 + hstep, voffB); PG8_STAGE(PG8_SA(1, 0), a3, voffA);
;             PG8_WAIT_V(8); PG8_WAIT_L(0); PG8_BAR; PG8_MMA(1, 0, At, B0); PG8_MMA(1, 1, At, B1); PG8_BAR; PG8_SCHED;
	ds_read_b128 v[144:147], v142
	ds_read_b128 v[152:155], v142 offset:1024
	ds_read_b128 v[156:159], v142 offset:2048
	ds_read_b128 v[160:163], v142 offset:3072
	ds_read_b128 v[164:167], v143
	ds_read_b128 v[168:171], v143 offset:1024
	ds_read_b128 v[172:175], v143 offset:2048
	ds_read_b128 v[176:179], v143 offset:3072
	s_add_u32 s48, s48, 0x100000
	s_addc_u32 s49, s49, 0
	s_mov_b32 m0, s58
	s_nop 0
	ds_read_b128 v[180:183], v151 offset:32768
	ds_read_b128 v[184:187], v151 offset:33792
	ds_read_b128 v[188:191], v151 offset:34816
	ds_read_b128 v[192:195], v151 offset:35840
	ds_read_b128 v[196:199], v151 offset:36864
	ds_read_b128 v[200:203], v151 offset:37888
	ds_read_b128 v[204:207], v151 offset:38912
	ds_read_b128 v[208:211], v151 offset:39936
	global_load_lds_dwordx4 v134, s[48:49]
	s_mov_b32 m0, s59
	s_nop 0
	global_load_lds_dwordx4 v130, s[48:49]
	s_waitcnt vmcnt(8) lgkmcnt(0)
	s_barrier
	v_mfma_f32_16x16x32_bf16 v[124:127], v[144:147], v[180:183], v[124:127]
	v_mfma_f32_16x16x32_bf16 v[124:127], v[152:155], v[184:187], v[124:127]
	v_mfma_f32_16x16x32_bf16 v[120:123], v[160:163], v[184:187], v[120:123]
	v_mfma_f32_16x16x32_bf16 v[120:123], v[156:159], v[180:183], v[120:123]
	v_mfma_f32_16x16x32_bf16 v[104:107], v[156:159], v[188:191], v[104:107]
	v_mfma_f32_16x16x32_bf16 v[104:107], v[160:163], v[192:195], v[104:107]
	v_mfma_f32_16x16x32_bf16 v[108:111], v[152:155], v[192:195], v[108:111]
	v_mfma_f32_16x16x32_bf16 v[108:111], v[144:147], v[188:191], v[108:111]
	v_mfma_f32_16x16x32_bf16 v[92:95], v[144:147], v[196:199], v[92:95]
	v_mfma_f32_16x16x32_bf16 v[92:95], v[152:155], v[200:203], v[92:95]
	v_mfma_f32_16x16x32_bf16 v[88:91], v[160:163], v[200:203], v[88:91]
	v_mfma_f32_16x16x32_bf16 v[88:91], v[156:159], v[196:199], v[88:91]
	v_mfma_f32_16x16x32_bf16 v[72:75], v[156:159], v[204:207], v[72:75]
	v_mfma_f32_16x16x32_bf16 v[72:75], v[160:163], v[208:211], v[72:75]
	v_mfma_f32_16x16x32_bf16 v[76:79], v[152:155], v[208:211], v[76:79]
	v_mfma_f32_16x16x32_bf16 v[76:79], v[144:147], v[204:207], v[76:79]
	v_mfma_f32_16x16x32_bf16 v[116:119], v[164:167], v[180:183], v[116:119]
	v_mfma_f32_16x16x32_bf16 v[116:119], v[168:171], v[184:187], v[116:119]
	v_mfma_f32_16x16x32_bf16 v[112:115], v[176:179], v[184:187], v[112:115]
	v_mfma_f32_16x16x32_bf16 v[112:115], v[172:175], v[180:183], v[112:115]
	v_mfma_f32_16x16x32_bf16 v[96:99], v[172:175], v[188:191], v[96:99]
	v_mfma_f32_16x16x32_bf16 v[96:99], v[176:179], v[192:195], v[96:99]
	v_mfma_f32_16x16x32_bf16 v[100:103], v[168:171], v[192:195], v[100:103]
	v_mfma_f32_16x16x32_bf16 v[100:103], v[164:167], v[188:191], v[100:103]
	v_mfma_f32_16x16x32_bf16 v[84:87], v[164:167], v[196:199], v[84:87]
	v_mfma_f32_16x16x32_bf16 v[84:87], v[168:171], v[200:203], v[84:87]
	v_mfma_f32_16x16x32_bf16 v[80:83], v[176:179], v[200:203], v[80:83]
	v_mfma_f32_16x16x32_bf16 v[80:83], v[172:175], v[196:199], v[80:83]
	v_mfma_f32_16x16x32_bf16 v[64:67], v[172:175], v[204:207], v[64:67]
	v_mfma_f32_16x16x32_bf16 v[64:67], v[176:179], v[208:211], v[64:67]
	v_mfma_f32_16x16x32_bf16 v[68:71], v[168:171], v[208:211], v[68:71]
	v_mfma_f32_16x16x32_bf16 v[68:71], v[164:167], v[204:207], v[68:71]
	s_barrier
	s_mov_b32 m0, s82
	s_nop 0
	s_add_u32 s94, s46, 0x80
	s_addc_u32 s95, s47, 0
	s_add_u32 s46, s46, 0x100080
	ds_read_b128 v[180:183], v151 offset:49152
	ds_read_b128 v[184:187], v151 offset:50176
	ds_read_b128 v[188:191], v151 offset:51200
	ds_read_b128 v[192:195], v151 offset:52224
	ds_read_b128 v[196:199], v151 offset:53248
	ds_read_b128 v[200:203], v151 offset:54272
	ds_read_b128 v[204:207], v151 offset:55296
	ds_read_b128 v[208:211], v151 offset:56320
	global_load_lds_dwordx4 v132, s[94:95]
	s_mov_b32 m0, s83
	s_addc_u32 s47, s47, 0
	global_load_lds_dwordx4 v128, s[94:95]
	s_mov_b32 m0, s84
	s_nop 0
	global_load_lds_dwordx4 v132, s[46:47]
	s_mov_b32 m0, s85
	s_nop 0
	global_load_lds_dwordx4 v128, s[46:47]
	s_mov_b32 m0, s62
	s_nop 0
	s_add_u32 s96, s48, 0xfff00080
	s_addc_u32 s97, s49, -1
	global_load_lds_dwordx4 v134, s[96:97]
	s_mov_b32 m0, s63
	s_nop 0
	global_load_lds_dwordx4 v130, s[96:97]
	s_waitcnt vmcnt(8) lgkmcnt(0)
	s_barrier
	v_mfma_f32_16x16x32_bf16 v[60:63], v[144:147], v[180:183], v[60:63]
	v_mfma_f32_16x16x32_bf16 v[60:63], v[152:155], v[184:187], v[60:63]
	v_mfma_f32_16x16x32_bf16 v[56:59], v[160:163], v[184:187], v[56:59]
	v_mfma_f32_16x16x32_bf16 v[56:59], v[156:159], v[180:183], v[56:59]
	v_mfma_f32_16x16x32_bf16 v[40:43], v[156:159], v[188:191], v[40:43]
	v_mfma_f32_16x16x32_bf16 v[40:43], v[160:163], v[192:195], v[40:43]
	v_mfma_f32_16x16x32_bf16 v[44:47], v[152:155], v[192:195], v[44:47]
	v_mfma_f32_16x16x32_bf16 v[44:47], v[144:147], v[188:191], v[44:47]
	v_mfma_f32_16x16x32_bf16 v[28:31], v[144:147], v[196:199], v[28:31]
	v_mfma_f32_16x16x32_bf16 v[28:31], v[152:155], v[200:203], v[28:31]
	v_mfma_f32_16x16x32_bf16 v[24:27], v[160:163], v[200:203], v[24:27]
	v_mfma_f32_16x16x32_bf16 v[24:27], v[156:159], v[196:199], v[24:27]
	v_mfma_f32_16x16x32_bf16 v[8:11], v[156:159], v[204:207], v[8:11]
	v_mfma_f32_16x16x32_bf16 v[8:11], v[160:163], v[208:211], v[8:11]
	v_mfma_f32_16x16x32_bf16 v[12:15], v[152:155], v[208:211], v[12:15]
	v_mfma_f32_16x16x32_bf16 v[12:15], v[144:147], v[204:207], v[12:15]
	v_mfma_f32_16x16x32_bf16 v[52:55], v[164:167], v[180:183], v[52:55]
	v_mfma_f32_16x16x32_bf16 v[52:55], v[168:171], v[184:187], v[52:55]
	v_mfma_f32_16x16x32_bf16 v[48:51], v[176:179], v[184:187], v[48:51]
	v_mfma_f32_16x16x32_bf16 v[48:51], v[172:175], v[180:183], v[48:51]
	v_mfma_f32_16x16x32_bf16 v[32:35], v[172:175], v[188:191], v[32:35]
	v_mfma_f32_16x16x32_bf16 v[32:35], v[176:179], v[192:195], v[32:35]
	v_mfma_f32_16x16x32_bf16 v[36:39], v[168:171], v[192:195], v[36:39]
	v_mfma_f32_16x16x32_bf16 v[36:39], v[164:167], v[188:191], v[36:39]
	v_mfma_f32_16x16x32_bf16 v[20:23], v[164:167], v[196:199], v[20:23]
	v_mfma_f32_16x16x32_bf16 v[20:23], v[168:171], v[200:203], v[20:23]
	v_mfma_f32_16x16x32_bf16 v[16:19], v[176:179], v[200:203], v[16:19]
	v_mfma_f32_16x16x32_bf16 v[16:19], v[172:175], v[196:199], v[16:19]
	v_mfma_f32_16x16x32_bf16 v[0:3], v[172:175], v[204:207], v[0:3]
	v_mfma_f32_16x16x32_bf16 v[0:3], v[176:179], v[208:211], v[0:3]
	v_mfma_f32_16x16x32_bf16 v[4:7], v[168:171], v[208:211], v[4:7]
	v_mfma_f32_16x16x32_bf16 v[4:7], v[164:167], v[204:207], v[4:7]
	s_barrier
	s_add_i32 s88, s88, 2
	s_add_u32 s44, s44, 0x100
	s_addc_u32 s45, s45, 0
	s_add_u32 s86, s86, 0x100
	s_addc_u32 s87, s87, 0
	s_cmp_gt_u32 s88, 61
	s_cbranch_scc0 .LBB0_1343
	s_and_b64 vcc, exec, s[14:15]
	s_cbranch_vccz .LBB0_1346
	s_barrier

; #define PG8_LAS __attribute__((address_space(3)))
; #define PG8_STAGE(bufoff, gbase, voff) do { _Pragma("unroll") for (int _i = 0; _i < 2; ++_i) \
;         __builtin_amdgcn_global_load_lds((const unsigned*)((const char*)(gbase) + (voff)[_i]), (PG8_LAS unsigned*)(lds + (bufoff) + ldsw + _i * 8192), 16, 0, 0); } while (0)
; #define PG8_LDA(dst, b, h) do { _Pragma("unroll") for (int m = 0; m < 4; ++m) _Pragma("unroll") for (int k = 0; k < 2; ++k) dst[m][k] = *(const PG8_LAS bf16x8*)(lds + PG8_SA(b, h) + aoff + m * 2048 + k * 1024); } while (0)
; #define PG8_LDB(dst, b, h) do { _Pragma("unroll") for (int n = 0; n < 2; ++n) _Pragma("unroll") for (int k = 0; k < 2; ++k) dst[n][k] = *(const PG8_LAS bf16x8*)(lds + PG8_SB(b, h) + boff + n * 2048 + k * 1024); } while (0)
; #define PG8_WAIT_V(n) asm volatile("s_waitcnt vmcnt(" #n ")" ::: "memory")
; #define PG8_WAIT_L(n) asm volatile("s_waitcnt lgkmcnt(" #n ")" ::: "memory")
; #define PG8_BAR __builtin_amdgcn_s_barrier()
; #define PG8_SCHED __builtin_amdgcn_sched_barrier(0)
; template <class Epi, class Sched, bool ALIGN_EPI = false, bool SP2 = false>
; __device__ __forceinline__ void gemm_phase(PG8_LAS unsigned char* lds, const Gemm g, const Sched& S, const Epi& E, int wave_s) {
;     ...
;             const bool last = (t == nt - 2);
;             if constexpr (Epi::NEED_RS) { if (t == 0 && wid < 4) __builtin_amdgcn_global_load_lds((const unsigned*)(E.rstd + cur.pm * BM + wid * 64 + lane), (PG8_LAS unsigned*)(rsl + wid * 64), 4, 0, 0); }
;             const char* a1 = cA + (size_t)(t + 1) * kstep;
;             const char* a2 = last ? nA : cA + (size_t)(t + 2) * kstep; const char* b2 = last ? nB : cB + (size_t)(t + 2) * kstep;
;             const char* a3 = a2 + kstep; const char* b3 = b2 + kstep;
;             if (last && has_next) S.a_ready(nxt);
;             if constexpr (SP2) {
;             PG8_LDB(B0, 0, 0); PG8_LDB(B1, 0, 1); PG8_SCHED; PG8_LDA(At, 0, 0); PG8_STAGE(PG8_SA(1, 1), a1 + hstep, voffA);
;             PG8_WAIT_V(8); PG8_WAIT_L(0); PG8_BAR; PG8_MMA(0, 0, At, B0); PG8_MMA(0, 1, At, B1); PG8_BAR; PG8_SCHED;
;             PG8_LDA(At, 0, 1); PG8_STAGE(PG8_SB(0, 0), b2, voffB); PG8_STAGE(PG8_SB(0, 1), b2 + hstep, voffB); PG8_STAGE(PG8_SA(0, 0), a2, voffA);
;             PG8_WAIT_V(8); PG8_WAIT_L(0); PG8_BAR; PG8_MMA(1, 0, At, B0); PG8_MMA(1, 1, At, B1); PG8_BAR; PG8_SCHED;
.LBB0_1410:
	ds_read_b128 v[128:131], v211
	ds_read_b128 v[132:135], v211 offset:1024
	ds_read_b128 v[136:139], v211 offset:2048
	ds_read_b128 v[140:143], v211 offset:3072
	ds_read_b128 v[144:147], v212
	ds_read_b128 v[148:151], v212 offset:1024
	ds_read_b128 v[152:155], v212 offset:2048
	ds_read_b128 v[156:159], v212 offset:3072
	s_add_u32 s45, s50, 0xffc00080
	s_addc_u32 s52, s51, -1
	s_cmp_eq_u32 s85, s43
	s_cselect_b32 s55, s47, s52
	s_cselect_b32 s54, s46, s45
	s_cselect_b32 s53, s49, s41
	s_cselect_b32 s52, s48, s7
	s_add_i32 m0, s9, 0xc000
	ds_read_b128 v[160:163], v213
	ds_read_b128 v[164:167], v213 offset:1024
	ds_read_b128 v[168:171], v213 offset:2048
	ds_read_b128 v[172:175], v213 offset:3072
	ds_read_b128 v[176:179], v213 offset:4096
	ds_read_b128 v[180:183], v213 offset:5120
	ds_read_b128 v[196:199], v213 offset:6144
	ds_read_b128 v[200:203], v213 offset:7168
	global_load_lds_dwordx4 v192, s[50:51]
	s_add_i32 m0, s9, 0xe000
	s_nop 0
	global_load_lds_dwordx4 v194, s[50:51]
	s_waitcnt vmcnt(8) lgkmcnt(0)
	s_barrier
	v_mfma_f32_16x16x32_bf16 v[124:127], v[128:131], v[160:163], v[124:127]
	v_mfma_f32_16x16x32_bf16 v[124:127], v[132:135], v[164:167], v[124:127]
	v_mfma_f32_16x16x32_bf16 v[120:123], v[140:143], v[164:167], v[120:123]
	v_mfma_f32_16x16x32_bf16 v[120:123], v[136:139], v[160:163], v[120:123]
	v_mfma_f32_16x16x32_bf16 v[104:107], v[136:139], v[168:171], v[104:107]
	v_mfma_f32_16x16x32_bf16 v[104:107], v[140:143], v[172:175], v[104:107]
	v_mfma_f32_16x16x32_bf16 v[108:111], v[132:135], v[172:175], v[108:111]
	v_mfma_f32_16x16x32_bf16 v[108:111], v[128:131], v[168:171], v[108:111]
	v_mfma_f32_16x16x32_bf16 v[92:95], v[128:131], v[176:179], v[92:95]
	v_mfma_f32_16x16x32_bf16 v[92:95], v[132:135], v[180:183], v[92:95]
	v_mfma_f32_16x16x32_bf16 v[88:91], v[140:143], v[180:183], v[88:91]
	v_mfma_f32_16x16x32_bf16 v[88:91], v[136:139], v[176:179], v[88:91]
	v_mfma_f32_16x16x32_bf16 v[72:75], v[136:139], v[196:199], v[72:75]
	v_mfma_f32_16x16x32_bf16 v[72:75], v[140:143], v[200:203], v[72:75]
	v_mfma_f32_16x16x32_bf16 v[76:79], v[132:135], v[200:203], v[76:79]
	v_mfma_f32_16x16x32_bf16 v[76:79], v[128:131], v[196:199], v[76:79]
	v_mfma_f32_16x16x32_bf16 v[116:119], v[144:147], v[160:163], v[116:119]
	v_mfma_f32_16x16x32_bf16 v[116:119], v[148:151], v[164:167], v[116:119]
	v_mfma_f32_16x16x32_bf16 v[112:115], v[156:159], v[164:167], v[112:115]
	v_mfma_f32_16x16x32_bf16 v[112:115], v[152:155], v[160:163], v[112:115]
	v_mfma_f32_16x16x32_bf16 v[96:99], v[152:155], v[168:171], v[96:99]
	v_mfma_f32_16x16x32_bf16 v[96:99], v[156:159], v[172:175], v[96:99]
	v_mfma_f32_16x16x32_bf16 v[100:103], v[148:151], v[172:175], v[100:103]
	v_mfma_f32_16x16x32_bf16 v[100:103], v[144:147], v[168:171], v[100:103]
	v_mfma_f32_16x16x32_bf16 v[84:87], v[144:147], v[176:179], v[84:87]
	v_mfma_f32_16x16x32_bf16 v[84:87], v[148:151], v[180:183], v[84:87]
	v_mfma_f32_16x16x32_bf16 v[80:83], v[156:159], v[180:183], v[80:83]
	v_mfma_f32_16x16x32_bf16 v[80:83], v[152:155], v[176:179], v[80:83]
	v_mfma_f32_16x16x32_bf16 v[64:67], v[152:155], v[196:199], v[64:67]
	v_mfma_f32_16x16x32_bf16 v[64:67], v[156:159], v[200:203], v[64:67]
	v_mfma_f32_16x16x32_bf16 v[68:71], v[148:151], v[200:203], v[68:71]
	v_mfma_f32_16x16x32_bf16 v[68:71], v[144:147], v[196:199], v[68:71]
	s_barrier
	s_add_i32 s45, s75, s60
	s_mov_b32 m0, s45
	ds_read_b128 v[160:163], v213 offset:16384
	ds_read_b128 v[164:167], v213 offset:17408
	ds_read_b128 v[168:171], v213 offset:18432
	ds_read_b128 v[172:175], v213 offset:19456
	ds_read_b128 v[176:179], v213 offset:20480
	ds_read_b128 v[180:183], v213 offset:21504
	ds_read_b128 v[196:199], v213 offset:22528
	ds_read_b128 v[200:203], v213 offset:23552
	global_load_lds_dwordx4 v186, s[52:53]
	s_add_i32 m0, s45, 0x2000
	s_add_u32 s86, s52, 0x400000
	s_addc_u32 s87, s53, 0
	s_add_i32 s45, s76, s60
	global_load_lds_dwordx4 v190, s[52:53]
	s_mov_b32 m0, s45
	s_nop 0
	global_load_lds_dwordx4 v186, s[86:87]
	s_add_i32 m0, s45, 0x2000
	s_nop 0
	global_load_lds_dwordx4 v190, s[86:87]
	s_mov_b32 m0, s9
	s_nop 0
	global_load_lds_dwordx4 v184, s[54:55]
	s_mov_b32 m0, s61
	s_nop 0
	global_load_lds_dwordx4 v188, s[54:55]
	s_waitcnt vmcnt(8) lgkmcnt(0)
	s_barrier
	v_mfma_f32_16x16x32_bf16 v[60:63], v[128:131], v[160:163], v[60:63]
	v_mfma_f32_16x16x32_bf16 v[60:63], v[132:135], v[164:167], v[60:63]
	v_mfma_f32_16x16x32_bf16 v[56:59], v[140:143], v[164:167], v[56:59]
	v_mfma_f32_16x16x32_bf16 v[56:59], v[136:139], v[160:163], v[56:59]
	v_mfma_f32_16x16x32_bf16 v[40:43], v[136:139], v[168:171], v[40:43]
	v_mfma_f32_16x16x32_bf16 v[40:43], v[140:143], v[172:175], v[40:43]
	v_mfma_f32_16x16x32_bf16 v[44:47], v[132:135], v[172:175], v[44:47]
	v_mfma_f32_16x16x32_bf16 v[44:47], v[128:131], v[168:171], v[44:47]
	v_mfma_f32_16x16x32_bf16 v[28:31], v[128:131], v[176:179], v[28:31]
	v_mfma_f32_16x16x32_bf16 v[28:31], v[132:135], v[180:183], v[28:31]
	v_mfma_f32_16x16x32_bf16 v[24:27], v[140:143], v[180:183], v[24:27]
	v_mfma_f32_16x16x32_bf16 v[24:27], v[136:139], v[176:179], v[24:27]
	v_mfma_f32_16x16x32_bf16 v[8:11], v[136:139], v[196:199], v[8:11]
	v_mfma_f32_16x16x32_bf16 v[8:11], v[140:143], v[200:203], v[8:11]
	v_mfma_f32_16x16x32_bf16 v[12:15], v[132:135], v[200:203], v[12:15]
	v_mfma_f32_16x16x32_bf16 v[12:15], v[128:131], v[196:199], v[12:15]
	v_mfma_f32_16x16x32_bf16 v[52:55], v[144:147], v[160:163], v[52:55]
	v_mfma_f32_16x16x32_bf16 v[52:55], v[148:151], v[164:167], v[52:55]
	v_mfma_f32_16x16x32_bf16 v[48:51], v[156:159], v[164:167], v[48:51]
	v_mfma_f32_16x16x32_bf16 v[48:51], v[152:155], v[160:163], v[48:51]
	v_mfma_f32_16x16x32_bf16 v[32:35], v[152:155], v[168:171], v[32:35]
	v_mfma_f32_16x16x32_bf16 v[32:35], v[156:159], v[172:175], v[32:35]
	v_mfma_f32_16x16x32_bf16 v[36:39], v[148:151], v[172:175], v[36:39]
	v_mfma_f32_16x16x32_bf16 v[36:39], v[144:147], v[168:171], v[36:39]
	v_mfma_f32_16x16x32_bf16 v[20:23], v[144:147], v[176:179], v[20:23]
	v_mfma_f32_16x16x32_bf16 v[20:23], v[148:151], v[180:183], v[20:23]
	v_mfma_f32_16x16x32_bf16 v[16:19], v[156:159], v[180:183], v[16:19]
	v_mfma_f32_16x16x32_bf16 v[16:19], v[152:155], v[176:179], v[16:19]
	v_mfma_f32_16x16x32_bf16 v[0:3], v[152:155], v[196:199], v[0:3]
	v_mfma_f32_16x16x32_bf16 v[0:3], v[156:159], v[200:203], v[0:3]
	v_mfma_f32_16x16x32_bf16 v[4:7], v[148:151], v[200:203], v[4:7]
	v_mfma_f32_16x16x32_bf16 v[4:7], v[144:147], v[196:199], v[4:7]
	s_barrier
; #define PG8_STAGE(bufoff, gbase, voff) do { _Pragma("unroll") for (int _i = 0; _i < 2; ++_i) \
;         __builtin_amdgcn_global_load_lds((const unsigned*)((const char*)(gbase) + (voff)[_i]), (PG8_LAS unsigned*)(lds + (bufoff) + ldsw + _i * 8192), 16, 0, 0); } while (0)
; #define PG8_LDA(dst, b, h) do { _Pragma("unroll") for (int m = 0; m < 4; ++m) _Pragma("unroll") for (int k = 0; k < 2; ++k) dst[m][k] = *(const PG8_LAS bf16x8*)(lds + PG8_SA(b, h) + aoff + m * 2048 + k * 1024); } while (0)
; #define PG8_LDB(dst, b, h) do { _Pragma("unroll") for (int n = 0; n < 2; ++n) _Pragma("unroll") for (int k = 0; k < 2; ++k) dst[n][k] = *(const PG8_LAS bf16x8*)(lds + PG8_SB(b, h) + boff + n * 2048 + k * 1024); } while (0)
; #define PG8_MMA(ai, bj, At, Bt) do { __builtin_amdgcn_s_setprio(1); _Pragma("unroll") for (int m = 0; m < 4; ++m) _Pragma("unroll") for (int n = 0; n < 2; ++n) _Pragma("unroll") for (int k = 0; k < 2; ++k) \
;         acc[ai][bj][m][n] = __builtin_amdgcn_mfma_f32_16x16x32_bf16(Bt[n][k], At[m][k], acc[ai][bj][m][n], 0, 0, 0); __builtin_amdgcn_s_setprio(0); } while (0)
; #define PG8_WAIT_V(n) asm volatile("s_waitcnt vmcnt(" #n ")" ::: "memory")
; #define PG8_WAIT_L(n) asm volatile("s_waitcnt lgkmcnt(" #n ")" ::: "memory")
; #define PG8_BAR __builtin_amdgcn_s_barrier()
; #define PG8_SCHED __builtin_amdgcn_sched_barrier(0)
; template <class Epi, class Sched, bool ALIGN_EPI = false, bool SP2 = false>
; __device__ __forceinline__ void gemm_phase(PG8_LAS unsigned char* lds, const Gemm g, const Sched& S, const Epi& E, int wave_s) {
;     ...
;             PG8_LDB(B0, 1, 0); PG8_LDB(B1, 1, 1); PG8_SCHED; PG8_LDA(At, 1, 0); PG8_STAGE(PG8_SA(0, 1), a2 + hstep, voffA);
;             PG8_WAIT_V(8); PG8_WAIT_L(0); PG8_BAR; PG8_MMA(0, 0, At, B0); PG8_MMA(0, 1, At, B1); PG8_BAR; PG8_SCHED;
;             PG8_LDA(At, 1, 1); PG8_STAGE(PG8_SB(1, 0), b3, voffB); PG8_STAGE(PG8_SB(1, 1), b3 + hstep, voffB); PG8_STAGE(PG8_SA(1, 0), a3, voffA);
;             PG8_WAIT_V(8); PG8_WAIT_L(0); PG8_BAR; PG8_MMA(1, 0, At, B0); PG8_MMA(1, 1, At, B1); PG8_BAR; PG8_SCHED;
	s_add_i32 s45, 0, 0x18000
	s_add_i32 s86, 0, 0x1c000
	v_add_u32_e32 v140, s45, v210
	v_add_u32_e32 v156, s86, v210
	ds_read_b128 v[128:131], v140
	ds_read_b128 v[132:135], v140 offset:1024
	ds_read_b128 v[136:139], v140 offset:2048
	ds_read_b128 v[140:143], v140 offset:3072
	ds_read_b128 v[144:147], v156
	ds_read_b128 v[148:151], v156 offset:1024
	ds_read_b128 v[152:155], v156 offset:2048
	ds_read_b128 v[156:159], v156 offset:3072
	s_add_u32 s54, s54, 0x400000
	s_addc_u32 s55, s55, 0
	s_mov_b32 m0, s62
	s_nop 0
	ds_read_b128 v[160:163], v213 offset:32768
	ds_read_b128 v[164:167], v213 offset:33792
	ds_read_b128 v[168:171], v213 offset:34816
	ds_read_b128 v[172:175], v213 offset:35840
	ds_read_b128 v[176:179], v213 offset:36864
	ds_read_b128 v[180:183], v213 offset:37888
	ds_read_b128 v[196:199], v213 offset:38912
	ds_read_b128 v[200:203], v213 offset:39936
	global_load_lds_dwordx4 v184, s[54:55]
	s_mov_b32 m0, s63
	s_nop 0
	global_load_lds_dwordx4 v188, s[54:55]
	s_waitcnt vmcnt(8) lgkmcnt(0)
	s_barrier
	v_mfma_f32_16x16x32_bf16 v[124:127], v[128:131], v[160:163], v[124:127]
	v_mfma_f32_16x16x32_bf16 v[124:127], v[132:135], v[164:167], v[124:127]
	v_mfma_f32_16x16x32_bf16 v[120:123], v[140:143], v[164:167], v[120:123]
	v_mfma_f32_16x16x32_bf16 v[120:123], v[136:139], v[160:163], v[120:123]
	v_mfma_f32_16x16x32_bf16 v[104:107], v[136:139], v[168:171], v[104:107]
	v_mfma_f32_16x16x32_bf16 v[104:107], v[140:143], v[172:175], v[104:107]
	v_mfma_f32_16x16x32_bf16 v[108:111], v[132:135], v[172:175], v[108:111]
	v_mfma_f32_16x16x32_bf16 v[108:111], v[128:131], v[168:171], v[108:111]
	v_mfma_f32_16x16x32_bf16 v[92:95], v[128:131], v[176:179], v[92:95]
	v_mfma_f32_16x16x32_bf16 v[92:95], v[132:135], v[180:183], v[92:95]
	v_mfma_f32_16x16x32_bf16 v[88:91], v[140:143], v[180:183], v[88:91]
	v_mfma_f32_16x16x32_bf16 v[88:91], v[136:139], v[176:179], v[88:91]
	v_mfma_f32_16x16x32_bf16 v[72:75], v[136:139], v[196:199], v[72:75]
	v_mfma_f32_16x16x32_bf16 v[72:75], v[140:143], v[200:203], v[72:75]
	v_mfma_f32_16x16x32_bf16 v[76:79], v[132:135], v[200:203], v[76:79]
	v_mfma_f32_16x16x32_bf16 v[76:79], v[128:131], v[196:199], v[76:79]
	v_mfma_f32_16x16x32_bf16 v[116:119], v[144:147], v[160:163], v[116:119]
	v_mfma_f32_16x16x32_bf16 v[116:119], v[148:151], v[164:167], v[116:119]
	v_mfma_f32_16x16x32_bf16 v[112:115], v[156:159], v[164:167], v[112:115]
	v_mfma_f32_16x16x32_bf16 v[112:115], v[152:155], v[160:163], v[112:115]
	v_mfma_f32_16x16x32_bf16 v[96:99], v[152:155], v[168:171], v[96:99]
	v_mfma_f32_16x16x32_bf16 v[96:99], v[156:159], v[172:175], v[96:99]
	v_mfma_f32_16x16x32_bf16 v[100:103], v[148:151], v[172:175], v[100:103]
	v_mfma_f32_16x16x32_bf16 v[100:103], v[144:147], v[168:171], v[100:103]
	v_mfma_f32_16x16x32_bf16 v[84:87], v[144:147], v[176:179], v[84:87]
	v_mfma_f32_16x16x32_bf16 v[84:87], v[148:151], v[180:183], v[84:87]
	v_mfma_f32_16x16x32_bf16 v[80:83], v[156:159], v[180:183], v[80:83]
	v_mfma_f32_16x16x32_bf16 v[80:83], v[152:155], v[176:179], v[80:83]
	v_mfma_f32_16x16x32_bf16 v[64:67], v[152:155], v[196:199], v[64:67]
	v_mfma_f32_16x16x32_bf16 v[64:67], v[156:159], v[200:203], v[64:67]
	v_mfma_f32_16x16x32_bf16 v[68:71], v[148:151], v[200:203], v[68:71]
	v_mfma_f32_16x16x32_bf16 v[68:71], v[144:147], v[196:199], v[68:71]
	s_barrier
	s_add_i32 s45, s45, s60
	s_mov_b32 m0, s45
	ds_read_b128 v[160:163], v213 offset:49152
	ds_read_b128 v[164:167], v213 offset:50176
	ds_read_b128 v[168:171], v213 offset:51200
	ds_read_b128 v[172:175], v213 offset:52224
	ds_read_b128 v[176:179], v213 offset:53248
	ds_read_b128 v[180:183], v213 offset:54272
	ds_read_b128 v[196:199], v213 offset:55296
	ds_read_b128 v[200:203], v213 offset:56320
	s_add_u32 s94, s52, 0x80
	s_addc_u32 s95, s53, 0
	global_load_lds_dwordx4 v186, s[94:95]
	s_add_i32 m0, s45, 0x2000
	s_add_u32 s52, s52, 0x400080
	s_addc_u32 s53, s53, 0
	s_add_i32 s45, s86, s60
	global_load_lds_dwordx4 v190, s[94:95]
	s_mov_b32 m0, s45
	s_nop 0
	global_load_lds_dwordx4 v186, s[52:53]
	s_add_i32 m0, s45, 0x2000
	s_nop 0
	global_load_lds_dwordx4 v190, s[52:53]
	s_mov_b32 m0, s70
	s_nop 0
	s_add_u32 s96, s54, 0xffc00080
	s_addc_u32 s97, s55, -1
	global_load_lds_dwordx4 v184, s[96:97]
	s_mov_b32 m0, s71
	s_nop 0
	global_load_lds_dwordx4 v188, s[96:97]
	s_waitcnt vmcnt(8) lgkmcnt(0)
	s_barrier
	v_mfma_f32_16x16x32_bf16 v[60:63], v[128:131], v[160:163], v[60:63]
	v_mfma_f32_16x16x32_bf16 v[60:63], v[132:135], v[164:167], v[60:63]
	v_mfma_f32_16x16x32_bf16 v[56:59], v[140:143], v[164:167], v[56:59]
	v_mfma_f32_16x16x32_bf16 v[56:59], v[136:139], v[160:163], v[56:59]
	v_mfma_f32_16x16x32_bf16 v[40:43], v[136:139], v[168:171], v[40:43]
	v_mfma_f32_16x16x32_bf16 v[40:43], v[140:143], v[172:175], v[40:43]
	v_mfma_f32_16x16x32_bf16 v[44:47], v[132:135], v[172:175], v[44:47]
	v_mfma_f32_16x16x32_bf16 v[44:47], v[128:131], v[168:171], v[44:47]
	v_mfma_f32_16x16x32_bf16 v[28:31], v[128:131], v[176:179], v[28:31]
	v_mfma_f32_16x16x32_bf16 v[28:31], v[132:135], v[180:183], v[28:31]
	v_mfma_f32_16x16x32_bf16 v[24:27], v[140:143], v[180:183], v[24:27]
	v_mfma_f32_16x16x32_bf16 v[24:27], v[136:139], v[176:179], v[24:27]
	v_mfma_f32_16x16x32_bf16 v[8:11], v[136:139], v[196:199], v[8:11]
	v_mfma_f32_16x16x32_bf16 v[8:11], v[140:143], v[200:203], v[8:11]
	v_mfma_f32_16x16x32_bf16 v[12:15], v[132:135], v[200:203], v[12:15]
	v_mfma_f32_16x16x32_bf16 v[12:15], v[128:131], v[196:199], v[12:15]
	v_mfma_f32_16x16x32_bf16 v[52:55], v[144:147], v[160:163], v[52:55]
	v_mfma_f32_16x16x32_bf16 v[52:55], v[148:151], v[164:167], v[52:55]
	v_mfma_f32_16x16x32_bf16 v[48:51], v[156:159], v[164:167], v[48:51]
	v_mfma_f32_16x16x32_bf16 v[48:51], v[152:155], v[160:163], v[48:51]
	v_mfma_f32_16x16x32_bf16 v[32:35], v[152:155], v[168:171], v[32:35]
	v_mfma_f32_16x16x32_bf16 v[32:35], v[156:159], v[172:175], v[32:35]
	v_mfma_f32_16x16x32_bf16 v[36:39], v[148:151], v[172:175], v[36:39]
	v_mfma_f32_16x16x32_bf16 v[36:39], v[144:147], v[168:171], v[36:39]
	v_mfma_f32_16x16x32_bf16 v[20:23], v[144:147], v[176:179], v[20:23]
	v_mfma_f32_16x16x32_bf16 v[20:23], v[148:151], v[180:183], v[20:23]
	v_mfma_f32_16x16x32_bf16 v[16:19], v[156:159], v[180:183], v[16:19]
	v_mfma_f32_16x16x32_bf16 v[16:19], v[152:155], v[176:179], v[16:19]
	v_mfma_f32_16x16x32_bf16 v[0:3], v[152:155], v[196:199], v[0:3]
	v_mfma_f32_16x16x32_bf16 v[0:3], v[156:159], v[200:203], v[0:3]
	v_mfma_f32_16x16x32_bf16 v[4:7], v[148:151], v[200:203], v[4:7]
	v_mfma_f32_16x16x32_bf16 v[4:7], v[144:147], v[196:199], v[4:7]
	s_barrier
	s_add_i32 s45, s43, 2
	s_add_u32 s50, s50, 0x100
	s_addc_u32 s51, s51, 0
	s_add_u32 s7, s7, 0x100
	s_addc_u32 s41, s41, 0
	s_cmp_ge_i32 s43, s85
	s_mov_b32 s43, s45
	s_cbranch_scc0 .LBB0_1410
	s_and_b64 vcc, exec, s[20:21]
	s_cbranch_vccz .LBB0_1413
	s_barrier
